# P3 v9: all LDS-DMA issued by the 4 staging waves, state decay multiply moved to the end of the previous step (off the read->MFMA chain)
# baseline (speedup 1.0000x reference)
; #define LAS __attribute__((address_space(3)))
; __device__ __forceinline__ void gla_scan_item(const Ctx& C, int item, LAS unsigned char* lds, int tid) {
;     const int jx = item >> 3, bh = (item & 7) * 4 + (jx >> 3), sl = jx & 7, b = bh >> 2, h = bh & 3;
;     LAS bf16* Aq = (LAS bf16*)lds;
;     LAS bf16* Bc = (LAS bf16*)(lds + 25600);
;     LAS bf16* Kt = (LAS bf16*)(lds + 38400);
;     const int wave = tid >> 6, lane = tid & 63, l15 = lane & 15, quad = lane >> 4;
;     f32x4 S[2] = {(f32x4){0.f, 0.f, 0.f, 0.f}, (f32x4){0.f, 0.f, 0.f, 0.f}};
;     *(LAS u32x4*)(Bc + (tid >> 4) * 200 + (tid & 15) * 8) = (u32x4){0u, 0u, 0u, 0u};
;     u32x4 rq0A, rq1A, rsA, rk0A, rk1A, rvA = (u32x4){0u, 0u, 0u, 0u}; f32x4 rdA;
;     u32x4 rq0B, rq1B, rsB, rk0B, rk1B, rvB = (u32x4){0u, 0u, 0u, 0u}; f32x4 rdB;
.LBB0_428:
	s_cmp_lt_i32 s96, 4
	s_cselect_b64 s[4:5], -1, 0
	s_add_u32 s6, s94, 0xb300000
	s_addc_u32 s7, s95, 0
	s_and_b64 s[0:1], s[4:5], s[0:1]
	s_andn2_b64 vcc, exec, s[0:1]
	s_cbranch_vccnz .LBB0_496
	s_cmpk_gt_i32 s2, 0xff
	s_cbranch_scc1 .LBB0_496
	v_readfirstlane_b32 s32, v163
	v_and_b32_e32 v208, 63, v162
	v_and_b32_e32 v207, 15, v162
	v_bfe_u32 v206, v162, 4, 2
	v_and_b32_e32 v202, 3, v163
	v_lshlrev_b32_e32 v202, 1, v202
	v_lshrrev_b32_e32 v205, 4, v208
	v_lshl_add_u32 v205, v202, 3, v205
	v_and_b32_e32 v204, 15, v205
	v_xor_b32_e32 v204, v204, v207
	v_lshlrev_b32_e32 v201, 10, v205
	v_lshl_add_u32 v201, v204, 4, v201
	v_lshrrev_b32_e32 v205, 4, v208
	v_lshl_add_u32 v205, v202, 3, v205
	v_add_u32_e32 v205, 4, v205
	v_and_b32_e32 v204, 15, v205
	v_xor_b32_e32 v204, v204, v207
	v_lshlrev_b32_e32 v200, 10, v205
	v_lshl_add_u32 v200, v204, 4, v200
	v_lshrrev_b32_e32 v205, 3, v208
	v_lshl_add_u32 v205, v202, 3, v205
	v_bfe_u32 v204, v205, 1, 3
	v_and_b32_e32 v203, 7, v208
	v_xor_b32_e32 v204, v204, v203
	v_lshlrev_b32_e32 v197, 7, v205
	v_lshl_add_u32 v197, v204, 4, v197
	v_lshrrev_b32_e32 v205, 3, v208
	v_lshl_add_u32 v205, v202, 4, v205
	v_bfe_u32 v204, v205, 1, 3
	v_and_b32_e32 v203, 7, v208
	v_xor_b32_e32 v204, v204, v203
	v_lshlrev_b32_e32 v195, 7, v205
	v_lshl_add_u32 v195, v204, 4, v195
	v_lshrrev_b32_e32 v205, 3, v208
	v_lshl_add_u32 v205, v202, 4, v205
	v_add_u32_e32 v205, 8, v205
	v_bfe_u32 v204, v205, 1, 3
	v_and_b32_e32 v203, 7, v208
	v_xor_b32_e32 v204, v204, v203
	v_lshlrev_b32_e32 v194, 7, v205
	v_lshl_add_u32 v194, v204, 4, v194
	v_add_u32_e32 v202, 1, v202
	v_lshrrev_b32_e32 v205, 4, v208
	v_lshl_add_u32 v205, v202, 3, v205
	v_and_b32_e32 v204, 15, v205
	v_xor_b32_e32 v204, v204, v207
	v_lshlrev_b32_e32 v199, 10, v205
	v_lshl_add_u32 v199, v204, 4, v199
	v_lshrrev_b32_e32 v205, 4, v208
	v_lshl_add_u32 v205, v202, 3, v205
	v_add_u32_e32 v205, 4, v205
	v_and_b32_e32 v204, 15, v205
	v_xor_b32_e32 v204, v204, v207
	v_lshlrev_b32_e32 v198, 10, v205
	v_lshl_add_u32 v198, v204, 4, v198
	v_lshrrev_b32_e32 v205, 3, v208
	v_lshl_add_u32 v205, v202, 3, v205
	v_bfe_u32 v204, v205, 1, 3
	v_and_b32_e32 v203, 7, v208
	v_xor_b32_e32 v204, v204, v203
	v_lshlrev_b32_e32 v196, 7, v205
	v_lshl_add_u32 v196, v204, 4, v196
	v_lshrrev_b32_e32 v205, 3, v208
	v_lshl_add_u32 v205, v202, 4, v205
	v_bfe_u32 v204, v205, 1, 3
	v_and_b32_e32 v203, 7, v208
	v_xor_b32_e32 v204, v204, v203
	v_lshlrev_b32_e32 v193, 7, v205
	v_lshl_add_u32 v193, v204, 4, v193
	v_lshrrev_b32_e32 v205, 3, v208
	v_lshl_add_u32 v205, v202, 4, v205
	v_add_u32_e32 v205, 8, v205
	v_bfe_u32 v204, v205, 1, 3
	v_and_b32_e32 v203, 7, v208
	v_xor_b32_e32 v204, v204, v203
	v_lshlrev_b32_e32 v192, 7, v205
	v_lshl_add_u32 v192, v204, 4, v192
	s_and_b32 s4, s32, 3
	s_lshl_b32 s46, s4, 12
	s_lshl_b32 s47, s4, 11
	s_add_i32 s47, s47, 0x4000
	s_add_i32 s48, s46, 0x6000
	v_and_b32_e32 v205, 1, v163
	v_lshl_add_u32 v205, v205, 5, v207
	v_or_b32_e32 v204, 0, v206
	v_and_b32_e32 v203, 15, v205
	v_xor_b32_e32 v204, v204, v203
	v_lshlrev_b32_e32 v246, 8, v205
	v_lshl_add_u32 v246, v204, 4, v246
	v_or_b32_e32 v204, 4, v206
	v_and_b32_e32 v203, 15, v205
	v_xor_b32_e32 v204, v204, v203
	v_lshlrev_b32_e32 v245, 8, v205
	v_lshl_add_u32 v245, v204, 4, v245
	v_or_b32_e32 v204, 8, v206
	v_and_b32_e32 v203, 15, v205
	v_xor_b32_e32 v204, v204, v203
	v_lshlrev_b32_e32 v244, 8, v205
	v_lshl_add_u32 v244, v204, 4, v244
	v_or_b32_e32 v204, 12, v206
	v_and_b32_e32 v203, 15, v205
	v_xor_b32_e32 v204, v204, v203
	v_lshlrev_b32_e32 v243, 8, v205
	v_lshl_add_u32 v243, v204, 4, v243
	v_or_b32_e32 v204, 0, v206
	v_bfe_u32 v203, v205, 1, 3
	v_xor_b32_e32 v204, v204, v203
	v_lshlrev_b32_e32 v238, 7, v205
	v_lshl_add_u32 v238, v204, 4, v238
	v_add_u32_e32 v238, 0x4000, v238
	v_or_b32_e32 v204, 4, v206
	v_bfe_u32 v203, v205, 1, 3
	v_xor_b32_e32 v204, v204, v203
	v_lshlrev_b32_e32 v235, 7, v205
	v_lshl_add_u32 v235, v204, 4, v235
	v_add_u32_e32 v235, 0x4000, v235
	v_lshlrev_b32_e32 v253, 11, v205
	v_lshl_add_u32 v253, v206, 3, v253
	v_add_u32_e32 v252, 0x8000, v253
	v_or_b32_e32 v204, 0, v206
	v_and_b32_e32 v203, 15, v207
	v_xor_b32_e32 v204, v204, v203
	v_lshlrev_b32_e32 v228, 8, v207
	v_lshl_add_u32 v228, v204, 4, v228
	v_add_u32_e32 v228, 0x1e000, v228
	v_or_b32_e32 v204, 4, v206
	v_and_b32_e32 v203, 15, v207
	v_xor_b32_e32 v204, v204, v203
	v_lshlrev_b32_e32 v227, 8, v207
	v_lshl_add_u32 v227, v204, 4, v227
	v_add_u32_e32 v227, 0x1e000, v227
	v_or_b32_e32 v204, 8, v206
	v_and_b32_e32 v203, 15, v207
	v_xor_b32_e32 v204, v204, v203
	v_lshlrev_b32_e32 v226, 8, v207
	v_lshl_add_u32 v226, v204, 4, v226
	v_add_u32_e32 v226, 0x1e000, v226
	v_or_b32_e32 v204, 12, v206
	v_and_b32_e32 v203, 15, v207
	v_xor_b32_e32 v204, v204, v203
	v_lshlrev_b32_e32 v225, 8, v207
	v_lshl_add_u32 v225, v204, 4, v225
	v_add_u32_e32 v225, 0x1e000, v225
	v_or_b32_e32 v204, 0, v206
	v_bfe_u32 v203, v207, 1, 3
	v_xor_b32_e32 v204, v204, v203
	v_lshlrev_b32_e32 v224, 7, v207
	v_lshl_add_u32 v224, v204, 4, v224
	v_add_u32_e32 v224, 0x20100, v224
	v_or_b32_e32 v204, 4, v206
	v_bfe_u32 v203, v207, 1, 3
	v_xor_b32_e32 v204, v204, v203
	v_lshlrev_b32_e32 v223, 7, v207
	v_lshl_add_u32 v223, v204, 4, v223
	v_add_u32_e32 v223, 0x20100, v223
	v_and_b32_e32 v205, 1, v163
	v_lshl_add_u32 v205, v205, 6, v207
	v_or_b32_e32 v204, 0, v206
	v_bfe_u32 v203, v205, 1, 3
; #define LAS __attribute__((address_space(3)))
; __device__ __forceinline__ void gla_scan_item(const Ctx& C, int item, LAS unsigned char* lds, int tid) {
;     ...
;     const int wave = tid >> 6, lane = tid & 63, l15 = lane & 15, quad = lane >> 4;
;     f32x4 S[2] = {(f32x4){0.f, 0.f, 0.f, 0.f}, (f32x4){0.f, 0.f, 0.f, 0.f}};
;     *(LAS u32x4*)(Bc + (tid >> 4) * 200 + (tid & 15) * 8) = (u32x4){0u, 0u, 0u, 0u};
;     u32x4 rq0A, rq1A, rsA, rk0A, rk1A, rvA = (u32x4){0u, 0u, 0u, 0u}; f32x4 rdA;
;     u32x4 rq0B, rq1B, rsB, rk0B, rk1B, rvB = (u32x4){0u, 0u, 0u, 0u}; f32x4 rdB;
	v_xor_b32_e32 v204, v204, v203
	v_lshlrev_b32_e32 v232, 7, v205
	v_lshl_add_u32 v232, v204, 4, v232
	v_add_u32_e32 v232, 0x6000, v232
	v_or_b32_e32 v204, 4, v206
	v_bfe_u32 v203, v205, 1, 3
	v_xor_b32_e32 v204, v204, v203
	v_lshlrev_b32_e32 v231, 7, v205
	v_lshl_add_u32 v231, v204, 4, v231
	v_add_u32_e32 v231, 0x6000, v231
	v_or_b32_e32 v204, 0, v206
	v_bfe_u32 v203, v207, 1, 3
	v_xor_b32_e32 v204, v204, v203
	v_lshlrev_b32_e32 v222, 7, v207
	v_lshl_add_u32 v222, v204, 4, v222
	v_add_u32_e32 v222, 0x20100, v222
	v_or_b32_e32 v204, 4, v206
	v_bfe_u32 v203, v207, 1, 3
	v_xor_b32_e32 v204, v204, v203
	v_lshlrev_b32_e32 v221, 7, v207
	v_lshl_add_u32 v221, v204, 4, v221
	v_add_u32_e32 v221, 0x20100, v221
	v_add_u32_e32 v242, 0x14000, v246
	v_add_u32_e32 v241, 0x14000, v245
	v_add_u32_e32 v240, 0x14000, v244
	v_add_u32_e32 v239, 0x14000, v243
	v_add_u32_e32 v234, 0x14000, v238
	v_add_u32_e32 v233, 0x14000, v235
	v_add_u32_e32 v230, 0x14000, v232
	v_add_u32_e32 v229, 0x14000, v231
	v_and_b32_e32 v205, 1, v163
	v_lshrrev_b32_e32 v204, 1, v206
	v_lshl_add_u32 v204, v205, 3, v204
	v_xor_b32_e32 v204, v204, v207
	v_lshlrev_b32_e32 v220, 8, v207
	v_lshl_add_u32 v220, v204, 4, v220
	v_and_b32_e32 v204, 1, v206
	v_lshl_add_u32 v220, v204, 3, v220
	v_add_u32_e32 v220, 0x1e000, v220
	v_and_b32_e32 v205, 1, v163
	v_lshrrev_b32_e32 v204, 1, v206
	v_lshl_add_u32 v204, v205, 3, v204
	v_add_u32_e32 v204, 2, v204
	v_xor_b32_e32 v204, v204, v207
	v_lshlrev_b32_e32 v219, 8, v207
	v_lshl_add_u32 v219, v204, 4, v219
	v_and_b32_e32 v204, 1, v206
	v_lshl_add_u32 v219, v204, 3, v219
	v_add_u32_e32 v219, 0x1e000, v219
	v_and_b32_e32 v205, 1, v163
	v_lshrrev_b32_e32 v204, 1, v206
	v_lshl_add_u32 v204, v205, 3, v204
	v_add_u32_e32 v204, 4, v204
	v_xor_b32_e32 v204, v204, v207
	v_lshlrev_b32_e32 v218, 8, v207
	v_lshl_add_u32 v218, v204, 4, v218
	v_and_b32_e32 v204, 1, v206
	v_lshl_add_u32 v218, v204, 3, v218
	v_add_u32_e32 v218, 0x1e000, v218
	v_and_b32_e32 v205, 1, v163
	v_lshrrev_b32_e32 v204, 1, v206
	v_lshl_add_u32 v204, v205, 3, v204
	v_add_u32_e32 v204, 6, v204
	v_xor_b32_e32 v204, v204, v207
	v_lshlrev_b32_e32 v217, 8, v207
	v_lshl_add_u32 v217, v204, 4, v217
	v_and_b32_e32 v204, 1, v206
	v_lshl_add_u32 v217, v204, 3, v217
	v_add_u32_e32 v217, 0x1e000, v217
	v_bfe_u32 v205, v162, 2, 6
	v_and_b32_e32 v203, 3, v162
	v_lshl_add_u32 v204, v203, 3, 0
	v_lshlrev_b32_e32 v216, 7, v204
	v_bfe_u32 v204, v204, 1, 3
	v_lshrrev_b32_e32 v251, 3, v205
	v_xor_b32_e32 v204, v204, v251
	v_lshl_add_u32 v216, v204, 4, v216
	v_and_b32_e32 v204, 7, v205
	v_lshl_add_u32 v216, v204, 1, v216
	v_add_u32_e32 v216, 0x20100, v216
	v_lshl_add_u32 v204, v203, 3, 1
	v_lshlrev_b32_e32 v215, 7, v204
	v_bfe_u32 v204, v204, 1, 3
	v_lshrrev_b32_e32 v251, 3, v205
	v_xor_b32_e32 v204, v204, v251
	v_lshl_add_u32 v215, v204, 4, v215
	v_and_b32_e32 v204, 7, v205
	v_lshl_add_u32 v215, v204, 1, v215
	v_add_u32_e32 v215, 0x20100, v215
	v_lshl_add_u32 v204, v203, 3, 2
	v_lshlrev_b32_e32 v214, 7, v204
	v_bfe_u32 v204, v204, 1, 3
	v_lshrrev_b32_e32 v251, 3, v205
	v_xor_b32_e32 v204, v204, v251
	v_lshl_add_u32 v214, v204, 4, v214
	v_and_b32_e32 v204, 7, v205
	v_lshl_add_u32 v214, v204, 1, v214
	v_add_u32_e32 v214, 0x20100, v214
	v_lshl_add_u32 v204, v203, 3, 3
	v_lshlrev_b32_e32 v213, 7, v204
	v_bfe_u32 v204, v204, 1, 3
	v_lshrrev_b32_e32 v251, 3, v205
	v_xor_b32_e32 v204, v204, v251
	v_lshl_add_u32 v213, v204, 4, v213
	v_and_b32_e32 v204, 7, v205
	v_lshl_add_u32 v213, v204, 1, v213
	v_add_u32_e32 v213, 0x20100, v213
	v_lshl_add_u32 v204, v203, 3, 4
	v_lshlrev_b32_e32 v212, 7, v204
	v_bfe_u32 v204, v204, 1, 3
	v_lshrrev_b32_e32 v251, 3, v205
	v_xor_b32_e32 v204, v204, v251
	v_lshl_add_u32 v212, v204, 4, v212
	v_and_b32_e32 v204, 7, v205
	v_lshl_add_u32 v212, v204, 1, v212
	v_add_u32_e32 v212, 0x20100, v212
	v_lshl_add_u32 v204, v203, 3, 5
	v_lshlrev_b32_e32 v211, 7, v204
	v_bfe_u32 v204, v204, 1, 3
	v_lshrrev_b32_e32 v251, 3, v205
	v_xor_b32_e32 v204, v204, v251
	v_lshl_add_u32 v211, v204, 4, v211
	v_and_b32_e32 v204, 7, v205
	v_lshl_add_u32 v211, v204, 1, v211
	v_add_u32_e32 v211, 0x20100, v211
	v_lshl_add_u32 v204, v203, 3, 6
	v_lshlrev_b32_e32 v210, 7, v204
	v_bfe_u32 v204, v204, 1, 3
	v_lshrrev_b32_e32 v251, 3, v205
	v_xor_b32_e32 v204, v204, v251
	v_lshl_add_u32 v210, v204, 4, v210
	v_and_b32_e32 v204, 7, v205
	v_lshl_add_u32 v210, v204, 1, v210
	v_add_u32_e32 v210, 0x20100, v210
	v_lshl_add_u32 v204, v203, 3, 7
	v_lshlrev_b32_e32 v209, 7, v204
	v_bfe_u32 v204, v204, 1, 3
	v_lshrrev_b32_e32 v251, 3, v205
	v_xor_b32_e32 v204, v204, v251
	v_lshl_add_u32 v209, v204, 4, v209
	v_and_b32_e32 v204, 7, v205
	v_lshl_add_u32 v209, v204, 1, v209
	v_add_u32_e32 v209, 0x20100, v209
	v_bfe_u32 v205, v162, 2, 6
	v_and_b32_e32 v204, 3, v162
	v_lshlrev_b32_e32 v255, 14, v205
	v_lshl_add_u32 v255, v204, 4, v255
	v_and_b32_e32 v205, 1, v163
	v_lshlrev_b32_e32 v254, 8, v205
	v_lshl_add_u32 v254, v206, 4, v254
	v_lshlrev_b32_e32 v250, 16, v205
	v_lshl_add_u32 v250, v206, 12, v250
	v_lshl_add_u32 v250, v207, 2, v250
	v_add_u32_e32 v249, 0x4000, v250
	v_add_u32_e32 v248, 0x8000, v250
	v_add_u32_e32 v247, 0xc000, v250
	v_lshlrev_b32_e32 v251, 4, v162
	v_add_u32_e32 v251, 0x1e000, v251
	v_mov_b32_e32 v8, 0
	v_mov_b32_e32 v9, 0
	v_mov_b32_e32 v10, 0
	v_mov_b32_e32 v11, 0
	s_cmp_gt_u32 s32, 3
	s_cbranch_scc1 .Lp3V_entry
	s_cmp_gt_u32 s32, 1
	s_cbranch_scc1 .Lp3S_entry

; #define LAS __attribute__((address_space(3)))
; __device__ __forceinline__ void gla_scan_item(const Ctx& C, int item, LAS unsigned char* lds, int tid) {
;     const int jx = item >> 3, bh = (item & 7) * 4 + (jx >> 3), sl = jx & 7, b = bh >> 2, h = bh & 3;
;     LAS bf16* Aq = (LAS bf16*)lds;
;     LAS bf16* Bc = (LAS bf16*)(lds + 25600);
;     LAS bf16* Kt = (LAS bf16*)(lds + 38400);
;     const int wave = tid >> 6, lane = tid & 63, l15 = lane & 15, quad = lane >> 4;
;     f32x4 S[2] = {(f32x4){0.f, 0.f, 0.f, 0.f}, (f32x4){0.f, 0.f, 0.f, 0.f}};
;     *(LAS u32x4*)(Bc + (tid >> 4) * 200 + (tid & 15) * 8) = (u32x4){0u, 0u, 0u, 0u};
;     u32x4 rq0A, rq1A, rsA, rk0A, rk1A, rvA = (u32x4){0u, 0u, 0u, 0u}; f32x4 rdA;
;     u32x4 rq0B, rq1B, rsB, rk0B, rk1B, rvB = (u32x4){0u, 0u, 0u, 0u}; f32x4 rdB;
.Lp3O_item:
	s_lshr_b32 s4, s3, 3
	s_and_b32 s41, s4, 7
	s_lshr_b32 s5, s4, 3
	s_and_b32 s37, s3, 7
	s_lshl_b32 s37, s37, 2
	s_add_i32 s37, s37, s5
	s_lshr_b32 s39, s37, 2
	s_and_b32 s40, s37, 3
	s_add_u32 s8, s94, 0x1d800000
	s_addc_u32 s9, s95, 0
	s_lshl_b32 s31, s39, 21
	s_add_u32 s8, s8, s31
	s_addc_u32 s9, s9, 0
	s_lshl_b32 s31, s40, 8
	s_add_u32 s8, s8, s31
	s_addc_u32 s9, s9, 0
	s_add_u32 s10, s94, 0x2f00000
	s_addc_u32 s11, s95, 0
	s_lshl_b32 s31, s37, 18
	s_add_u32 s10, s10, s31
	s_addc_u32 s11, s11, 0
	s_add_u32 s12, s94, 0x3700000
	s_addc_u32 s13, s95, 0
	s_lshl_b32 s31, s37, 19
	s_add_u32 s12, s12, s31
	s_addc_u32 s13, s13, 0
	s_add_u32 s18, s6, 0x0
	s_addc_u32 s19, s7, 0
	s_lshl_b32 s31, s39, 22
	s_add_u32 s18, s18, s31
	s_addc_u32 s19, s19, 0
	s_lshl_b32 s31, s40, 9
	s_add_u32 s18, s18, s31
	s_addc_u32 s19, s19, 0
	s_lshl_b32 s31, s41, 6
	s_add_u32 s18, s18, s31
	s_addc_u32 s19, s19, 0
	ds_write_b128 v251, v[8:11]
	s_waitcnt vmcnt(0)
	s_mov_b32 s33, 0
	s_waitcnt lgkmcnt(0)
	s_barrier
.Lp3O_loop:
	ds_read_b128 v[60:63], v246 offset:0
	ds_read_b128 v[12:15], v228 offset:0
	ds_read_b128 v[16:19], v228 offset:4096
	ds_read_b128 v[64:67], v246 offset:4096
	ds_read_b128 v[68:71], v245 offset:0
	ds_read_b128 v[20:23], v227 offset:0
	ds_read_b128 v[24:27], v227 offset:4096
	ds_read_b128 v[72:75], v245 offset:4096
	ds_read_b128 v[76:79], v244 offset:0
	ds_read_b128 v[28:31], v226 offset:0
	ds_read_b128 v[32:35], v226 offset:4096
	ds_read_b128 v[80:83], v244 offset:4096
	s_waitcnt lgkmcnt(8)
	v_mfma_f32_16x16x32_bf16 v[108:111], v[12:15], v[60:63], 0
	v_mfma_f32_16x16x32_bf16 v[112:115], v[16:19], v[60:63], 0
	v_mfma_f32_16x16x32_bf16 v[116:119], v[12:15], v[64:67], 0
	v_mfma_f32_16x16x32_bf16 v[120:123], v[16:19], v[64:67], 0
	ds_read_b128 v[84:87], v243 offset:0
	ds_read_b128 v[36:39], v225 offset:0
	ds_read_b128 v[40:43], v225 offset:4096
	ds_read_b128 v[88:91], v243 offset:4096
	s_waitcnt lgkmcnt(8)
	v_mfma_f32_16x16x32_bf16 v[108:111], v[20:23], v[68:71], v[108:111]
	v_mfma_f32_16x16x32_bf16 v[112:115], v[24:27], v[68:71], v[112:115]
	v_mfma_f32_16x16x32_bf16 v[116:119], v[20:23], v[72:75], v[116:119]
	v_mfma_f32_16x16x32_bf16 v[120:123], v[24:27], v[72:75], v[120:123]
	ds_read_b128 v[92:95], v238 offset:0
	ds_read_b128 v[44:47], v224 offset:0
	ds_read_b128 v[48:51], v224 offset:2048
	ds_read_b128 v[96:99], v238 offset:2048
	s_waitcnt lgkmcnt(8)
	v_mfma_f32_16x16x32_bf16 v[108:111], v[28:31], v[76:79], v[108:111]
	v_mfma_f32_16x16x32_bf16 v[112:115], v[32:35], v[76:79], v[112:115]
	v_mfma_f32_16x16x32_bf16 v[116:119], v[28:31], v[80:83], v[116:119]
	v_mfma_f32_16x16x32_bf16 v[120:123], v[32:35], v[80:83], v[120:123]
	ds_read_b128 v[100:103], v235 offset:0
	ds_read_b128 v[52:55], v223 offset:0
	ds_read_b128 v[56:59], v223 offset:2048
	ds_read_b128 v[104:107], v235 offset:2048
	s_waitcnt lgkmcnt(8)
	v_mfma_f32_16x16x32_bf16 v[108:111], v[36:39], v[84:87], v[108:111]
	v_mfma_f32_16x16x32_bf16 v[112:115], v[40:43], v[84:87], v[112:115]
	v_mfma_f32_16x16x32_bf16 v[116:119], v[36:39], v[88:91], v[116:119]
	v_mfma_f32_16x16x32_bf16 v[120:123], v[40:43], v[88:91], v[120:123]
	s_waitcnt lgkmcnt(4)
	v_mfma_f32_16x16x32_bf16 v[108:111], v[44:47], v[92:95], v[108:111]
	v_mfma_f32_16x16x32_bf16 v[112:115], v[48:51], v[92:95], v[112:115]
	v_mfma_f32_16x16x32_bf16 v[116:119], v[44:47], v[96:99], v[116:119]
	v_mfma_f32_16x16x32_bf16 v[120:123], v[48:51], v[96:99], v[120:123]
	s_waitcnt lgkmcnt(0)
	v_mfma_f32_16x16x32_bf16 v[108:111], v[52:55], v[100:103], v[108:111]
	v_mfma_f32_16x16x32_bf16 v[112:115], v[56:59], v[100:103], v[112:115]
	v_mfma_f32_16x16x32_bf16 v[116:119], v[52:55], v[104:107], v[116:119]
	v_mfma_f32_16x16x32_bf16 v[120:123], v[56:59], v[104:107], v[120:123]
	s_nop 7
	s_nop 7
	v_cvt_pk_bf16_f32 v124, v108, v109
	v_cvt_pk_bf16_f32 v125, v110, v111
	v_cvt_pk_bf16_f32 v126, v112, v113
	v_cvt_pk_bf16_f32 v127, v114, v115
	v_cvt_pk_bf16_f32 v128, v116, v117
	v_cvt_pk_bf16_f32 v129, v118, v119
	v_cvt_pk_bf16_f32 v130, v120, v121
	v_cvt_pk_bf16_f32 v131, v122, v123
	global_store_dwordx2 v253, v[124:125], s[18:19]
	global_store_dwordx2 v253, v[126:127], s[18:19] offset:32
	global_store_dwordx2 v252, v[128:129], s[18:19]
	global_store_dwordx2 v252, v[130:131], s[18:19] offset:32
	s_add_u32 s18, s18, 0x20000
	s_addc_u32 s19, s19, 0
	s_add_i32 s33, s33, 1
	s_waitcnt lgkmcnt(0)
	s_barrier
	ds_read_b128 v[60:63], v246 offset:40960
	ds_read_b128 v[12:15], v228 offset:12544
	ds_read_b128 v[16:19], v228 offset:16640
	ds_read_b128 v[64:67], v246 offset:45056
	ds_read_b128 v[68:71], v245 offset:40960
	ds_read_b128 v[20:23], v227 offset:12544
	ds_read_b128 v[24:27], v227 offset:16640
	ds_read_b128 v[72:75], v245 offset:45056
	ds_read_b128 v[76:79], v244 offset:40960
	ds_read_b128 v[28:31], v226 offset:12544
	ds_read_b128 v[32:35], v226 offset:16640
	ds_read_b128 v[80:83], v244 offset:45056
	s_waitcnt lgkmcnt(8)
	v_mfma_f32_16x16x32_bf16 v[108:111], v[12:15], v[60:63], 0
	v_mfma_f32_16x16x32_bf16 v[112:115], v[16:19], v[60:63], 0
	v_mfma_f32_16x16x32_bf16 v[116:119], v[12:15], v[64:67], 0
	v_mfma_f32_16x16x32_bf16 v[120:123], v[16:19], v[64:67], 0
	ds_read_b128 v[84:87], v243 offset:40960
	ds_read_b128 v[36:39], v225 offset:12544
	ds_read_b128 v[40:43], v225 offset:16640
	ds_read_b128 v[88:91], v243 offset:45056
	s_waitcnt lgkmcnt(8)
	v_mfma_f32_16x16x32_bf16 v[108:111], v[20:23], v[68:71], v[108:111]
	v_mfma_f32_16x16x32_bf16 v[112:115], v[24:27], v[68:71], v[112:115]
	v_mfma_f32_16x16x32_bf16 v[116:119], v[20:23], v[72:75], v[116:119]
	v_mfma_f32_16x16x32_bf16 v[120:123], v[24:27], v[72:75], v[120:123]
	ds_read_b128 v[92:95], v238 offset:40960
	ds_read_b128 v[44:47], v224 offset:12288
	ds_read_b128 v[48:51], v224 offset:14336
	ds_read_b128 v[96:99], v238 offset:43008
	s_waitcnt lgkmcnt(8)
	v_mfma_f32_16x16x32_bf16 v[108:111], v[28:31], v[76:79], v[108:111]
	v_mfma_f32_16x16x32_bf16 v[112:115], v[32:35], v[76:79], v[112:115]
	v_mfma_f32_16x16x32_bf16 v[116:119], v[28:31], v[80:83], v[116:119]
	v_mfma_f32_16x16x32_bf16 v[120:123], v[32:35], v[80:83], v[120:123]
	ds_read_b128 v[100:103], v235 offset:40960
	ds_read_b128 v[52:55], v223 offset:12288
	ds_read_b128 v[56:59], v223 offset:14336
	ds_read_b128 v[104:107], v235 offset:43008
	s_waitcnt lgkmcnt(8)
	v_mfma_f32_16x16x32_bf16 v[108:111], v[36:39], v[84:87], v[108:111]
	v_mfma_f32_16x16x32_bf16 v[112:115], v[40:43], v[84:87], v[112:115]
	v_mfma_f32_16x16x32_bf16 v[116:119], v[36:39], v[88:91], v[116:119]
	v_mfma_f32_16x16x32_bf16 v[120:123], v[40:43], v[88:91], v[120:123]
	s_waitcnt lgkmcnt(4)
	v_mfma_f32_16x16x32_bf16 v[108:111], v[44:47], v[92:95], v[108:111]
	v_mfma_f32_16x16x32_bf16 v[112:115], v[48:51], v[92:95], v[112:115]
	v_mfma_f32_16x16x32_bf16 v[116:119], v[44:47], v[96:99], v[116:119]
	v_mfma_f32_16x16x32_bf16 v[120:123], v[48:51], v[96:99], v[120:123]
	s_waitcnt lgkmcnt(0)
	v_mfma_f32_16x16x32_bf16 v[108:111], v[52:55], v[100:103], v[108:111]
	v_mfma_f32_16x16x32_bf16 v[112:115], v[56:59], v[100:103], v[112:115]
	v_mfma_f32_16x16x32_bf16 v[116:119], v[52:55], v[104:107], v[116:119]
	v_mfma_f32_16x16x32_bf16 v[120:123], v[56:59], v[104:107], v[120:123]
	s_nop 7
	s_nop 7
	v_cvt_pk_bf16_f32 v124, v108, v109
	v_cvt_pk_bf16_f32 v125, v110, v111
	v_cvt_pk_bf16_f32 v126, v112, v113
	v_cvt_pk_bf16_f32 v127, v114, v115
	v_cvt_pk_bf16_f32 v128, v116, v117
	v_cvt_pk_bf16_f32 v129, v118, v119
	v_cvt_pk_bf16_f32 v130, v120, v121
	v_cvt_pk_bf16_f32 v131, v122, v123
	global_store_dwordx2 v253, v[124:125], s[18:19]
	global_store_dwordx2 v253, v[126:127], s[18:19] offset:32
	global_store_dwordx2 v252, v[128:129], s[18:19]
	global_store_dwordx2 v252, v[130:131], s[18:19] offset:32
	s_add_u32 s18, s18, 0x20000
	s_addc_u32 s19, s19, 0
	s_add_i32 s33, s33, 1
	s_waitcnt lgkmcnt(0)
	s_barrier
	ds_read_b128 v[60:63], v242 offset:0
	ds_read_b128 v[12:15], v228 offset:0
	ds_read_b128 v[16:19], v228 offset:4096
	ds_read_b128 v[64:67], v242 offset:4096
	ds_read_b128 v[68:71], v241 offset:0
	ds_read_b128 v[20:23], v227 offset:0
	ds_read_b128 v[24:27], v227 offset:4096
	ds_read_b128 v[72:75], v241 offset:4096
	ds_read_b128 v[76:79], v240 offset:0
	ds_read_b128 v[28:31], v226 offset:0
	ds_read_b128 v[32:35], v226 offset:4096
	ds_read_b128 v[80:83], v240 offset:4096
	s_waitcnt lgkmcnt(8)
	v_mfma_f32_16x16x32_bf16 v[108:111], v[12:15], v[60:63], 0
	v_mfma_f32_16x16x32_bf16 v[112:115], v[16:19], v[60:63], 0
	v_mfma_f32_16x16x32_bf16 v[116:119], v[12:15], v[64:67], 0
	v_mfma_f32_16x16x32_bf16 v[120:123], v[16:19], v[64:67], 0
	ds_read_b128 v[84:87], v239 offset:0
	ds_read_b128 v[36:39], v225 offset:0
	ds_read_b128 v[40:43], v225 offset:4096
	ds_read_b128 v[88:91], v239 offset:4096
	s_waitcnt lgkmcnt(8)
	v_mfma_f32_16x16x32_bf16 v[108:111], v[20:23], v[68:71], v[108:111]
	v_mfma_f32_16x16x32_bf16 v[112:115], v[24:27], v[68:71], v[112:115]
	v_mfma_f32_16x16x32_bf16 v[116:119], v[20:23], v[72:75], v[116:119]
	v_mfma_f32_16x16x32_bf16 v[120:123], v[24:27], v[72:75], v[120:123]
	ds_read_b128 v[92:95], v234 offset:0
	ds_read_b128 v[44:47], v224 offset:0
	ds_read_b128 v[48:51], v224 offset:2048
	ds_read_b128 v[96:99], v234 offset:2048
	s_waitcnt lgkmcnt(8)
	v_mfma_f32_16x16x32_bf16 v[108:111], v[28:31], v[76:79], v[108:111]
	v_mfma_f32_16x16x32_bf16 v[112:115], v[32:35], v[76:79], v[112:115]
	v_mfma_f32_16x16x32_bf16 v[116:119], v[28:31], v[80:83], v[116:119]
	v_mfma_f32_16x16x32_bf16 v[120:123], v[32:35], v[80:83], v[120:123]
	ds_read_b128 v[100:103], v233 offset:0
	ds_read_b128 v[52:55], v223 offset:0
	ds_read_b128 v[56:59], v223 offset:2048
	ds_read_b128 v[104:107], v233 offset:2048
	s_waitcnt lgkmcnt(8)
	v_mfma_f32_16x16x32_bf16 v[108:111], v[36:39], v[84:87], v[108:111]
	v_mfma_f32_16x16x32_bf16 v[112:115], v[40:43], v[84:87], v[112:115]
	v_mfma_f32_16x16x32_bf16 v[116:119], v[36:39], v[88:91], v[116:119]
	v_mfma_f32_16x16x32_bf16 v[120:123], v[40:43], v[88:91], v[120:123]
	s_waitcnt lgkmcnt(4)
	v_mfma_f32_16x16x32_bf16 v[108:111], v[44:47], v[92:95], v[108:111]
	v_mfma_f32_16x16x32_bf16 v[112:115], v[48:51], v[92:95], v[112:115]
	v_mfma_f32_16x16x32_bf16 v[116:119], v[44:47], v[96:99], v[116:119]
	v_mfma_f32_16x16x32_bf16 v[120:123], v[48:51], v[96:99], v[120:123]
	s_waitcnt lgkmcnt(0)
	v_mfma_f32_16x16x32_bf16 v[108:111], v[52:55], v[100:103], v[108:111]
	v_mfma_f32_16x16x32_bf16 v[112:115], v[56:59], v[100:103], v[112:115]
	v_mfma_f32_16x16x32_bf16 v[116:119], v[52:55], v[104:107], v[116:119]
	v_mfma_f32_16x16x32_bf16 v[120:123], v[56:59], v[104:107], v[120:123]
	s_nop 7
	s_nop 7
	v_cvt_pk_bf16_f32 v124, v108, v109
	v_cvt_pk_bf16_f32 v125, v110, v111
	v_cvt_pk_bf16_f32 v126, v112, v113
	v_cvt_pk_bf16_f32 v127, v114, v115
	v_cvt_pk_bf16_f32 v128, v116, v117
	v_cvt_pk_bf16_f32 v129, v118, v119
	v_cvt_pk_bf16_f32 v130, v120, v121
	v_cvt_pk_bf16_f32 v131, v122, v123
	global_store_dwordx2 v253, v[124:125], s[18:19]
	global_store_dwordx2 v253, v[126:127], s[18:19] offset:32
	global_store_dwordx2 v252, v[128:129], s[18:19]
	global_store_dwordx2 v252, v[130:131], s[18:19] offset:32
	s_add_u32 s18, s18, 0x20000
	s_addc_u32 s19, s19, 0
	s_add_i32 s33, s33, 1
	s_waitcnt lgkmcnt(0)
	s_barrier
	ds_read_b128 v[60:63], v246 offset:0
	ds_read_b128 v[12:15], v228 offset:12544
	ds_read_b128 v[16:19], v228 offset:16640
	ds_read_b128 v[64:67], v246 offset:4096
	ds_read_b128 v[68:71], v245 offset:0
	ds_read_b128 v[20:23], v227 offset:12544
	ds_read_b128 v[24:27], v227 offset:16640
	ds_read_b128 v[72:75], v245 offset:4096
	ds_read_b128 v[76:79], v244 offset:0
	ds_read_b128 v[28:31], v226 offset:12544
	ds_read_b128 v[32:35], v226 offset:16640
	ds_read_b128 v[80:83], v244 offset:4096
	s_waitcnt lgkmcnt(8)
	v_mfma_f32_16x16x32_bf16 v[108:111], v[12:15], v[60:63], 0
	v_mfma_f32_16x16x32_bf16 v[112:115], v[16:19], v[60:63], 0
	v_mfma_f32_16x16x32_bf16 v[116:119], v[12:15], v[64:67], 0
	v_mfma_f32_16x16x32_bf16 v[120:123], v[16:19], v[64:67], 0
	ds_read_b128 v[84:87], v243 offset:0
	ds_read_b128 v[36:39], v225 offset:12544
	ds_read_b128 v[40:43], v225 offset:16640
	ds_read_b128 v[88:91], v243 offset:4096
	s_waitcnt lgkmcnt(8)
	v_mfma_f32_16x16x32_bf16 v[108:111], v[20:23], v[68:71], v[108:111]
	v_mfma_f32_16x16x32_bf16 v[112:115], v[24:27], v[68:71], v[112:115]
	v_mfma_f32_16x16x32_bf16 v[116:119], v[20:23], v[72:75], v[116:119]
	v_mfma_f32_16x16x32_bf16 v[120:123], v[24:27], v[72:75], v[120:123]
	ds_read_b128 v[92:95], v238 offset:0
	ds_read_b128 v[44:47], v224 offset:12288
	ds_read_b128 v[48:51], v224 offset:14336
	ds_read_b128 v[96:99], v238 offset:2048
	s_waitcnt lgkmcnt(8)
	v_mfma_f32_16x16x32_bf16 v[108:111], v[28:31], v[76:79], v[108:111]
	v_mfma_f32_16x16x32_bf16 v[112:115], v[32:35], v[76:79], v[112:115]
	v_mfma_f32_16x16x32_bf16 v[116:119], v[28:31], v[80:83], v[116:119]
	v_mfma_f32_16x16x32_bf16 v[120:123], v[32:35], v[80:83], v[120:123]
	ds_read_b128 v[100:103], v235 offset:0
	ds_read_b128 v[52:55], v223 offset:12288
	ds_read_b128 v[56:59], v223 offset:14336
	ds_read_b128 v[104:107], v235 offset:2048
	s_waitcnt lgkmcnt(8)
	v_mfma_f32_16x16x32_bf16 v[108:111], v[36:39], v[84:87], v[108:111]
	v_mfma_f32_16x16x32_bf16 v[112:115], v[40:43], v[84:87], v[112:115]
	v_mfma_f32_16x16x32_bf16 v[116:119], v[36:39], v[88:91], v[116:119]
	v_mfma_f32_16x16x32_bf16 v[120:123], v[40:43], v[88:91], v[120:123]
	s_waitcnt lgkmcnt(4)
	v_mfma_f32_16x16x32_bf16 v[108:111], v[44:47], v[92:95], v[108:111]
	v_mfma_f32_16x16x32_bf16 v[112:115], v[48:51], v[92:95], v[112:115]
	v_mfma_f32_16x16x32_bf16 v[116:119], v[44:47], v[96:99], v[116:119]
	v_mfma_f32_16x16x32_bf16 v[120:123], v[48:51], v[96:99], v[120:123]
	s_waitcnt lgkmcnt(0)
	v_mfma_f32_16x16x32_bf16 v[108:111], v[52:55], v[100:103], v[108:111]
	v_mfma_f32_16x16x32_bf16 v[112:115], v[56:59], v[100:103], v[112:115]
	v_mfma_f32_16x16x32_bf16 v[116:119], v[52:55], v[104:107], v[116:119]
	v_mfma_f32_16x16x32_bf16 v[120:123], v[56:59], v[104:107], v[120:123]
	s_nop 7
	s_nop 7
	v_cvt_pk_bf16_f32 v124, v108, v109
	v_cvt_pk_bf16_f32 v125, v110, v111
	v_cvt_pk_bf16_f32 v126, v112, v113
	v_cvt_pk_bf16_f32 v127, v114, v115
	v_cvt_pk_bf16_f32 v128, v116, v117
	v_cvt_pk_bf16_f32 v129, v118, v119
	v_cvt_pk_bf16_f32 v130, v120, v121
	v_cvt_pk_bf16_f32 v131, v122, v123
	global_store_dwordx2 v253, v[124:125], s[18:19]
	global_store_dwordx2 v253, v[126:127], s[18:19] offset:32
	global_store_dwordx2 v252, v[128:129], s[18:19]
	global_store_dwordx2 v252, v[130:131], s[18:19] offset:32
	s_add_u32 s18, s18, 0x20000
	s_addc_u32 s19, s19, 0
	s_add_i32 s33, s33, 1
	s_waitcnt lgkmcnt(0)
	s_barrier
	ds_read_b128 v[60:63], v246 offset:40960
	ds_read_b128 v[12:15], v228 offset:0
	ds_read_b128 v[16:19], v228 offset:4096
	ds_read_b128 v[64:67], v246 offset:45056
	ds_read_b128 v[68:71], v245 offset:40960
	ds_read_b128 v[20:23], v227 offset:0
	ds_read_b128 v[24:27], v227 offset:4096
	ds_read_b128 v[72:75], v245 offset:45056
	ds_read_b128 v[76:79], v244 offset:40960
	ds_read_b128 v[28:31], v226 offset:0
	ds_read_b128 v[32:35], v226 offset:4096
	ds_read_b128 v[80:83], v244 offset:45056
	s_waitcnt lgkmcnt(8)
	v_mfma_f32_16x16x32_bf16 v[108:111], v[12:15], v[60:63], 0
	v_mfma_f32_16x16x32_bf16 v[112:115], v[16:19], v[60:63], 0
	v_mfma_f32_16x16x32_bf16 v[116:119], v[12:15], v[64:67], 0
	v_mfma_f32_16x16x32_bf16 v[120:123], v[16:19], v[64:67], 0
	ds_read_b128 v[84:87], v243 offset:40960
	ds_read_b128 v[36:39], v225 offset:0
	ds_read_b128 v[40:43], v225 offset:4096
	ds_read_b128 v[88:91], v243 offset:45056
	s_waitcnt lgkmcnt(8)
	v_mfma_f32_16x16x32_bf16 v[108:111], v[20:23], v[68:71], v[108:111]
	v_mfma_f32_16x16x32_bf16 v[112:115], v[24:27], v[68:71], v[112:115]
	v_mfma_f32_16x16x32_bf16 v[116:119], v[20:23], v[72:75], v[116:119]
	v_mfma_f32_16x16x32_bf16 v[120:123], v[24:27], v[72:75], v[120:123]
	ds_read_b128 v[92:95], v238 offset:40960
	ds_read_b128 v[44:47], v224 offset:0
	ds_read_b128 v[48:51], v224 offset:2048
	ds_read_b128 v[96:99], v238 offset:43008
	s_waitcnt lgkmcnt(8)
	v_mfma_f32_16x16x32_bf16 v[108:111], v[28:31], v[76:79], v[108:111]
	v_mfma_f32_16x16x32_bf16 v[112:115], v[32:35], v[76:79], v[112:115]
	v_mfma_f32_16x16x32_bf16 v[116:119], v[28:31], v[80:83], v[116:119]
	v_mfma_f32_16x16x32_bf16 v[120:123], v[32:35], v[80:83], v[120:123]
	ds_read_b128 v[100:103], v235 offset:40960
	ds_read_b128 v[52:55], v223 offset:0
	ds_read_b128 v[56:59], v223 offset:2048
	ds_read_b128 v[104:107], v235 offset:43008
	s_waitcnt lgkmcnt(8)
	v_mfma_f32_16x16x32_bf16 v[108:111], v[36:39], v[84:87], v[108:111]
	v_mfma_f32_16x16x32_bf16 v[112:115], v[40:43], v[84:87], v[112:115]
	v_mfma_f32_16x16x32_bf16 v[116:119], v[36:39], v[88:91], v[116:119]
	v_mfma_f32_16x16x32_bf16 v[120:123], v[40:43], v[88:91], v[120:123]
	s_waitcnt lgkmcnt(4)
	v_mfma_f32_16x16x32_bf16 v[108:111], v[44:47], v[92:95], v[108:111]
	v_mfma_f32_16x16x32_bf16 v[112:115], v[48:51], v[92:95], v[112:115]
	v_mfma_f32_16x16x32_bf16 v[116:119], v[44:47], v[96:99], v[116:119]
	v_mfma_f32_16x16x32_bf16 v[120:123], v[48:51], v[96:99], v[120:123]
	s_waitcnt lgkmcnt(0)
	v_mfma_f32_16x16x32_bf16 v[108:111], v[52:55], v[100:103], v[108:111]
	v_mfma_f32_16x16x32_bf16 v[112:115], v[56:59], v[100:103], v[112:115]
	v_mfma_f32_16x16x32_bf16 v[116:119], v[52:55], v[104:107], v[116:119]
	v_mfma_f32_16x16x32_bf16 v[120:123], v[56:59], v[104:107], v[120:123]
	s_nop 7
	s_nop 7
	v_cvt_pk_bf16_f32 v124, v108, v109
	v_cvt_pk_bf16_f32 v125, v110, v111
	v_cvt_pk_bf16_f32 v126, v112, v113
	v_cvt_pk_bf16_f32 v127, v114, v115
	v_cvt_pk_bf16_f32 v128, v116, v117
	v_cvt_pk_bf16_f32 v129, v118, v119
	v_cvt_pk_bf16_f32 v130, v120, v121
	v_cvt_pk_bf16_f32 v131, v122, v123
	global_store_dwordx2 v253, v[124:125], s[18:19]
	global_store_dwordx2 v253, v[126:127], s[18:19] offset:32
	global_store_dwordx2 v252, v[128:129], s[18:19]
	global_store_dwordx2 v252, v[130:131], s[18:19] offset:32
	s_add_u32 s18, s18, 0x20000
	s_addc_u32 s19, s19, 0
	s_add_i32 s33, s33, 1
	s_waitcnt lgkmcnt(0)
	s_barrier
	ds_read_b128 v[60:63], v242 offset:0
	ds_read_b128 v[12:15], v228 offset:12544
	ds_read_b128 v[16:19], v228 offset:16640
	ds_read_b128 v[64:67], v242 offset:4096
	ds_read_b128 v[68:71], v241 offset:0
	ds_read_b128 v[20:23], v227 offset:12544
	ds_read_b128 v[24:27], v227 offset:16640
	ds_read_b128 v[72:75], v241 offset:4096
	ds_read_b128 v[76:79], v240 offset:0
	ds_read_b128 v[28:31], v226 offset:12544
	ds_read_b128 v[32:35], v226 offset:16640
	ds_read_b128 v[80:83], v240 offset:4096
	s_waitcnt lgkmcnt(8)
	v_mfma_f32_16x16x32_bf16 v[108:111], v[12:15], v[60:63], 0
	v_mfma_f32_16x16x32_bf16 v[112:115], v[16:19], v[60:63], 0
	v_mfma_f32_16x16x32_bf16 v[116:119], v[12:15], v[64:67], 0
	v_mfma_f32_16x16x32_bf16 v[120:123], v[16:19], v[64:67], 0
	ds_read_b128 v[84:87], v239 offset:0
	ds_read_b128 v[36:39], v225 offset:12544
	ds_read_b128 v[40:43], v225 offset:16640
	ds_read_b128 v[88:91], v239 offset:4096
	s_waitcnt lgkmcnt(8)
	v_mfma_f32_16x16x32_bf16 v[108:111], v[20:23], v[68:71], v[108:111]
	v_mfma_f32_16x16x32_bf16 v[112:115], v[24:27], v[68:71], v[112:115]
	v_mfma_f32_16x16x32_bf16 v[116:119], v[20:23], v[72:75], v[116:119]
	v_mfma_f32_16x16x32_bf16 v[120:123], v[24:27], v[72:75], v[120:123]
	ds_read_b128 v[92:95], v234 offset:0
	ds_read_b128 v[44:47], v224 offset:12288
	ds_read_b128 v[48:51], v224 offset:14336
	ds_read_b128 v[96:99], v234 offset:2048
	s_waitcnt lgkmcnt(8)
	v_mfma_f32_16x16x32_bf16 v[108:111], v[28:31], v[76:79], v[108:111]
	v_mfma_f32_16x16x32_bf16 v[112:115], v[32:35], v[76:79], v[112:115]
	v_mfma_f32_16x16x32_bf16 v[116:119], v[28:31], v[80:83], v[116:119]
	v_mfma_f32_16x16x32_bf16 v[120:123], v[32:35], v[80:83], v[120:123]
	ds_read_b128 v[100:103], v233 offset:0
	ds_read_b128 v[52:55], v223 offset:12288
	ds_read_b128 v[56:59], v223 offset:14336
	ds_read_b128 v[104:107], v233 offset:2048
	s_waitcnt lgkmcnt(8)
	v_mfma_f32_16x16x32_bf16 v[108:111], v[36:39], v[84:87], v[108:111]
	v_mfma_f32_16x16x32_bf16 v[112:115], v[40:43], v[84:87], v[112:115]
	v_mfma_f32_16x16x32_bf16 v[116:119], v[36:39], v[88:91], v[116:119]
	v_mfma_f32_16x16x32_bf16 v[120:123], v[40:43], v[88:91], v[120:123]
	s_waitcnt lgkmcnt(4)
	v_mfma_f32_16x16x32_bf16 v[108:111], v[44:47], v[92:95], v[108:111]
	v_mfma_f32_16x16x32_bf16 v[112:115], v[48:51], v[92:95], v[112:115]
	v_mfma_f32_16x16x32_bf16 v[116:119], v[44:47], v[96:99], v[116:119]
	v_mfma_f32_16x16x32_bf16 v[120:123], v[48:51], v[96:99], v[120:123]
	s_waitcnt lgkmcnt(0)
	v_mfma_f32_16x16x32_bf16 v[108:111], v[52:55], v[100:103], v[108:111]
	v_mfma_f32_16x16x32_bf16 v[112:115], v[56:59], v[100:103], v[112:115]
	v_mfma_f32_16x16x32_bf16 v[116:119], v[52:55], v[104:107], v[116:119]
	v_mfma_f32_16x16x32_bf16 v[120:123], v[56:59], v[104:107], v[120:123]
	s_nop 7
	s_nop 7
	v_cvt_pk_bf16_f32 v124, v108, v109
	v_cvt_pk_bf16_f32 v125, v110, v111
	v_cvt_pk_bf16_f32 v126, v112, v113
	v_cvt_pk_bf16_f32 v127, v114, v115
	v_cvt_pk_bf16_f32 v128, v116, v117
	v_cvt_pk_bf16_f32 v129, v118, v119
	v_cvt_pk_bf16_f32 v130, v120, v121
	v_cvt_pk_bf16_f32 v131, v122, v123
	global_store_dwordx2 v253, v[124:125], s[18:19]
	global_store_dwordx2 v253, v[126:127], s[18:19] offset:32
	global_store_dwordx2 v252, v[128:129], s[18:19]
	global_store_dwordx2 v252, v[130:131], s[18:19] offset:32
	s_add_u32 s18, s18, 0x20000
	s_addc_u32 s19, s19, 0
	s_add_i32 s33, s33, 1
	s_waitcnt lgkmcnt(0)
	s_barrier
	s_cmp_lt_u32 s33, 30
	s_cbranch_scc1 .Lp3O_loop
	ds_read_b128 v[60:63], v246 offset:0
	ds_read_b128 v[12:15], v228 offset:0
	ds_read_b128 v[16:19], v228 offset:4096
	ds_read_b128 v[64:67], v246 offset:4096
	ds_read_b128 v[68:71], v245 offset:0
	ds_read_b128 v[20:23], v227 offset:0
	ds_read_b128 v[24:27], v227 offset:4096
	ds_read_b128 v[72:75], v245 offset:4096
	ds_read_b128 v[76:79], v244 offset:0
	ds_read_b128 v[28:31], v226 offset:0
	ds_read_b128 v[32:35], v226 offset:4096
	ds_read_b128 v[80:83], v244 offset:4096
	s_waitcnt lgkmcnt(8)
	v_mfma_f32_16x16x32_bf16 v[108:111], v[12:15], v[60:63], 0
	v_mfma_f32_16x16x32_bf16 v[112:115], v[16:19], v[60:63], 0
	v_mfma_f32_16x16x32_bf16 v[116:119], v[12:15], v[64:67], 0
	v_mfma_f32_16x16x32_bf16 v[120:123], v[16:19], v[64:67], 0
	ds_read_b128 v[84:87], v243 offset:0
	ds_read_b128 v[36:39], v225 offset:0
	ds_read_b128 v[40:43], v225 offset:4096
	ds_read_b128 v[88:91], v243 offset:4096
	s_waitcnt lgkmcnt(8)
	v_mfma_f32_16x16x32_bf16 v[108:111], v[20:23], v[68:71], v[108:111]
	v_mfma_f32_16x16x32_bf16 v[112:115], v[24:27], v[68:71], v[112:115]
	v_mfma_f32_16x16x32_bf16 v[116:119], v[20:23], v[72:75], v[116:119]
	v_mfma_f32_16x16x32_bf16 v[120:123], v[24:27], v[72:75], v[120:123]
	ds_read_b128 v[92:95], v238 offset:0
	ds_read_b128 v[44:47], v224 offset:0
	ds_read_b128 v[48:51], v224 offset:2048
	ds_read_b128 v[96:99], v238 offset:2048
	s_waitcnt lgkmcnt(8)
	v_mfma_f32_16x16x32_bf16 v[108:111], v[28:31], v[76:79], v[108:111]
	v_mfma_f32_16x16x32_bf16 v[112:115], v[32:35], v[76:79], v[112:115]
	v_mfma_f32_16x16x32_bf16 v[116:119], v[28:31], v[80:83], v[116:119]
	v_mfma_f32_16x16x32_bf16 v[120:123], v[32:35], v[80:83], v[120:123]
	ds_read_b128 v[100:103], v235 offset:0
	ds_read_b128 v[52:55], v223 offset:0
	ds_read_b128 v[56:59], v223 offset:2048
	ds_read_b128 v[104:107], v235 offset:2048
	s_waitcnt lgkmcnt(8)
	v_mfma_f32_16x16x32_bf16 v[108:111], v[36:39], v[84:87], v[108:111]
	v_mfma_f32_16x16x32_bf16 v[112:115], v[40:43], v[84:87], v[112:115]
	v_mfma_f32_16x16x32_bf16 v[116:119], v[36:39], v[88:91], v[116:119]
	v_mfma_f32_16x16x32_bf16 v[120:123], v[40:43], v[88:91], v[120:123]
	s_waitcnt lgkmcnt(4)
	v_mfma_f32_16x16x32_bf16 v[108:111], v[44:47], v[92:95], v[108:111]
	v_mfma_f32_16x16x32_bf16 v[112:115], v[48:51], v[92:95], v[112:115]
	v_mfma_f32_16x16x32_bf16 v[116:119], v[44:47], v[96:99], v[116:119]
	v_mfma_f32_16x16x32_bf16 v[120:123], v[48:51], v[96:99], v[120:123]
	s_waitcnt lgkmcnt(0)
	v_mfma_f32_16x16x32_bf16 v[108:111], v[52:55], v[100:103], v[108:111]
	v_mfma_f32_16x16x32_bf16 v[112:115], v[56:59], v[100:103], v[112:115]
	v_mfma_f32_16x16x32_bf16 v[116:119], v[52:55], v[104:107], v[116:119]
	v_mfma_f32_16x16x32_bf16 v[120:123], v[56:59], v[104:107], v[120:123]
	s_nop 7
	s_nop 7
	v_cvt_pk_bf16_f32 v124, v108, v109
	v_cvt_pk_bf16_f32 v125, v110, v111
	v_cvt_pk_bf16_f32 v126, v112, v113
	v_cvt_pk_bf16_f32 v127, v114, v115
	v_cvt_pk_bf16_f32 v128, v116, v117
	v_cvt_pk_bf16_f32 v129, v118, v119
	v_cvt_pk_bf16_f32 v130, v120, v121
	v_cvt_pk_bf16_f32 v131, v122, v123
	global_store_dwordx2 v253, v[124:125], s[18:19]
	global_store_dwordx2 v253, v[126:127], s[18:19] offset:32
	global_store_dwordx2 v252, v[128:129], s[18:19]
	global_store_dwordx2 v252, v[130:131], s[18:19] offset:32
	s_add_u32 s18, s18, 0x20000
	s_addc_u32 s19, s19, 0
	s_add_i32 s33, s33, 1
	s_waitcnt lgkmcnt(0)
	s_barrier
	ds_read_b128 v[60:63], v246 offset:40960
	ds_read_b128 v[12:15], v228 offset:12544
	ds_read_b128 v[16:19], v228 offset:16640
	ds_read_b128 v[64:67], v246 offset:45056
	ds_read_b128 v[68:71], v245 offset:40960
	ds_read_b128 v[20:23], v227 offset:12544
	ds_read_b128 v[24:27], v227 offset:16640
	ds_read_b128 v[72:75], v245 offset:45056
	ds_read_b128 v[76:79], v244 offset:40960
	ds_read_b128 v[28:31], v226 offset:12544
	ds_read_b128 v[32:35], v226 offset:16640
	ds_read_b128 v[80:83], v244 offset:45056
	s_waitcnt lgkmcnt(8)
	v_mfma_f32_16x16x32_bf16 v[108:111], v[12:15], v[60:63], 0
	v_mfma_f32_16x16x32_bf16 v[112:115], v[16:19], v[60:63], 0
	v_mfma_f32_16x16x32_bf16 v[116:119], v[12:15], v[64:67], 0
	v_mfma_f32_16x16x32_bf16 v[120:123], v[16:19], v[64:67], 0
	ds_read_b128 v[84:87], v243 offset:40960
	ds_read_b128 v[36:39], v225 offset:12544
	ds_read_b128 v[40:43], v225 offset:16640
	ds_read_b128 v[88:91], v243 offset:45056
	s_waitcnt lgkmcnt(8)
	v_mfma_f32_16x16x32_bf16 v[108:111], v[20:23], v[68:71], v[108:111]
	v_mfma_f32_16x16x32_bf16 v[112:115], v[24:27], v[68:71], v[112:115]
	v_mfma_f32_16x16x32_bf16 v[116:119], v[20:23], v[72:75], v[116:119]
	v_mfma_f32_16x16x32_bf16 v[120:123], v[24:27], v[72:75], v[120:123]
	ds_read_b128 v[92:95], v238 offset:40960
	ds_read_b128 v[44:47], v224 offset:12288
	ds_read_b128 v[48:51], v224 offset:14336
	ds_read_b128 v[96:99], v238 offset:43008
	s_waitcnt lgkmcnt(8)
	v_mfma_f32_16x16x32_bf16 v[108:111], v[28:31], v[76:79], v[108:111]
	v_mfma_f32_16x16x32_bf16 v[112:115], v[32:35], v[76:79], v[112:115]
	v_mfma_f32_16x16x32_bf16 v[116:119], v[28:31], v[80:83], v[116:119]
	v_mfma_f32_16x16x32_bf16 v[120:123], v[32:35], v[80:83], v[120:123]
	ds_read_b128 v[100:103], v235 offset:40960
	ds_read_b128 v[52:55], v223 offset:12288
	ds_read_b128 v[56:59], v223 offset:14336
	ds_read_b128 v[104:107], v235 offset:43008
	s_waitcnt lgkmcnt(8)
	v_mfma_f32_16x16x32_bf16 v[108:111], v[36:39], v[84:87], v[108:111]
	v_mfma_f32_16x16x32_bf16 v[112:115], v[40:43], v[84:87], v[112:115]
	v_mfma_f32_16x16x32_bf16 v[116:119], v[36:39], v[88:91], v[116:119]
	v_mfma_f32_16x16x32_bf16 v[120:123], v[40:43], v[88:91], v[120:123]
	s_waitcnt lgkmcnt(4)
	v_mfma_f32_16x16x32_bf16 v[108:111], v[44:47], v[92:95], v[108:111]
	v_mfma_f32_16x16x32_bf16 v[112:115], v[48:51], v[92:95], v[112:115]
	v_mfma_f32_16x16x32_bf16 v[116:119], v[44:47], v[96:99], v[116:119]
	v_mfma_f32_16x16x32_bf16 v[120:123], v[48:51], v[96:99], v[120:123]
	s_waitcnt lgkmcnt(0)
	v_mfma_f32_16x16x32_bf16 v[108:111], v[52:55], v[100:103], v[108:111]
	v_mfma_f32_16x16x32_bf16 v[112:115], v[56:59], v[100:103], v[112:115]
	v_mfma_f32_16x16x32_bf16 v[116:119], v[52:55], v[104:107], v[116:119]
	v_mfma_f32_16x16x32_bf16 v[120:123], v[56:59], v[104:107], v[120:123]
	s_nop 7
	s_nop 7
	v_cvt_pk_bf16_f32 v124, v108, v109
	v_cvt_pk_bf16_f32 v125, v110, v111
	v_cvt_pk_bf16_f32 v126, v112, v113
	v_cvt_pk_bf16_f32 v127, v114, v115
	v_cvt_pk_bf16_f32 v128, v116, v117
	v_cvt_pk_bf16_f32 v129, v118, v119
	v_cvt_pk_bf16_f32 v130, v120, v121
	v_cvt_pk_bf16_f32 v131, v122, v123
	global_store_dwordx2 v253, v[124:125], s[18:19]
	global_store_dwordx2 v253, v[126:127], s[18:19] offset:32
	global_store_dwordx2 v252, v[128:129], s[18:19]
	global_store_dwordx2 v252, v[130:131], s[18:19] offset:32
	s_add_u32 s18, s18, 0x20000
	s_addc_u32 s19, s19, 0
	s_add_i32 s33, s33, 1
	s_waitcnt lgkmcnt(0)
	s_barrier
	s_waitcnt vmcnt(0) lgkmcnt(0)
	s_barrier
	s_add_i32 s3, s3, s42
	s_cmpk_lt_i32 s3, 0x100
	s_cbranch_scc1 .Lp3O_item
	s_branch .Lp3_done

; #define LAS __attribute__((address_space(3)))
; __device__ __forceinline__ void gla_scan_item(const Ctx& C, int item, LAS unsigned char* lds, int tid) {
;     const int jx = item >> 3, bh = (item & 7) * 4 + (jx >> 3), sl = jx & 7, b = bh >> 2, h = bh & 3;
;     LAS bf16* Aq = (LAS bf16*)lds;
;     LAS bf16* Bc = (LAS bf16*)(lds + 25600);
;     LAS bf16* Kt = (LAS bf16*)(lds + 38400);
;     const int wave = tid >> 6, lane = tid & 63, l15 = lane & 15, quad = lane >> 4;
;     f32x4 S[2] = {(f32x4){0.f, 0.f, 0.f, 0.f}, (f32x4){0.f, 0.f, 0.f, 0.f}};
;     *(LAS u32x4*)(Bc + (tid >> 4) * 200 + (tid & 15) * 8) = (u32x4){0u, 0u, 0u, 0u};
;     u32x4 rq0A, rq1A, rsA, rk0A, rk1A, rvA = (u32x4){0u, 0u, 0u, 0u}; f32x4 rdA;
;     u32x4 rq0B, rq1B, rsB, rk0B, rk1B, rvB = (u32x4){0u, 0u, 0u, 0u}; f32x4 rdB;
.Lp3S_item:
	s_lshr_b32 s4, s3, 3
	s_and_b32 s41, s4, 7
	s_lshr_b32 s5, s4, 3
	s_and_b32 s37, s3, 7
	s_lshl_b32 s37, s37, 2
	s_add_i32 s37, s37, s5
	s_lshr_b32 s39, s37, 2
	s_and_b32 s40, s37, 3
	s_add_u32 s8, s94, 0x1d800000
	s_addc_u32 s9, s95, 0
	s_lshl_b32 s31, s39, 21
	s_add_u32 s8, s8, s31
	s_addc_u32 s9, s9, 0
	s_lshl_b32 s31, s40, 8
	s_add_u32 s8, s8, s31
	s_addc_u32 s9, s9, 0
	s_add_u32 s10, s94, 0x2f00000
	s_addc_u32 s11, s95, 0
	s_lshl_b32 s31, s37, 18
	s_add_u32 s10, s10, s31
	s_addc_u32 s11, s11, 0
	s_add_u32 s12, s94, 0x3700000
	s_addc_u32 s13, s95, 0
	s_lshl_b32 s31, s37, 19
	s_add_u32 s12, s12, s31
	s_addc_u32 s13, s13, 0
	s_add_u32 s16, s94, 0x2e00000
	s_addc_u32 s17, s95, 0
	s_lshl_b32 s31, s37, 14
	s_add_u32 s16, s16, s31
	s_addc_u32 s17, s17, 0
	s_add_u32 s34, s92, 0x4090000
	s_addc_u32 s35, s93, 0
	s_lshl_b32 s31, s37, 17
	s_add_u32 s34, s34, s31
	s_addc_u32 s35, s35, 0
	s_lshl_b32 s31, s41, 7
	s_add_u32 s34, s34, s31
	s_addc_u32 s35, s35, 0
	v_mov_b32_e32 v60, 0
	v_mov_b32_e32 v61, 0
	v_mov_b32_e32 v62, 0
	v_mov_b32_e32 v63, 0
	v_mov_b32_e32 v64, 0
	v_mov_b32_e32 v65, 0
	v_mov_b32_e32 v66, 0
	v_mov_b32_e32 v67, 0
	v_mov_b32_e32 v68, 0
	v_mov_b32_e32 v69, 0
	v_mov_b32_e32 v70, 0
	v_mov_b32_e32 v71, 0
	v_mov_b32_e32 v72, 0
	v_mov_b32_e32 v73, 0
	v_mov_b32_e32 v74, 0
	v_mov_b32_e32 v75, 0
	v_mov_b32_e32 v76, 0
	v_mov_b32_e32 v77, 0
	v_mov_b32_e32 v78, 0
	v_mov_b32_e32 v79, 0
	v_mov_b32_e32 v80, 0
	v_mov_b32_e32 v81, 0
	v_mov_b32_e32 v82, 0
	v_mov_b32_e32 v83, 0
	v_mov_b32_e32 v84, 0
	v_mov_b32_e32 v85, 0
	v_mov_b32_e32 v86, 0
	v_mov_b32_e32 v87, 0
	v_mov_b32_e32 v88, 0
	v_mov_b32_e32 v89, 0
	v_mov_b32_e32 v90, 0
	v_mov_b32_e32 v91, 0
	ds_write_b128 v251, v[8:11]
	global_load_dwordx4 v[92:95], v254, s[16:17] offset:0
	global_load_dwordx4 v[96:99], v254, s[16:17] offset:64
	global_load_dwordx4 v[100:103], v254, s[16:17] offset:128
	global_load_dwordx4 v[104:107], v254, s[16:17] offset:192
	s_add_u32 s16, s16, 0x200
	s_addc_u32 s17, s17, 0
	global_load_dwordx4 v[108:111], v254, s[16:17] offset:0
	global_load_dwordx4 v[112:115], v254, s[16:17] offset:64
	global_load_dwordx4 v[116:119], v254, s[16:17] offset:128
	global_load_dwordx4 v[120:123], v254, s[16:17] offset:192
	s_add_u32 s16, s16, 0x200
	s_addc_u32 s17, s17, 0
	global_load_dwordx4 v[124:127], v254, s[16:17] offset:0
	global_load_dwordx4 v[128:131], v254, s[16:17] offset:64
	global_load_dwordx4 v[132:135], v254, s[16:17] offset:128
	global_load_dwordx4 v[136:139], v254, s[16:17] offset:192
	s_add_u32 s16, s16, 0x200
	s_addc_u32 s17, s17, 0
	s_waitcnt vmcnt(0)
	s_mov_b32 s33, 0
	s_waitcnt lgkmcnt(0)
	s_barrier
.Lp3S_loop:
	ds_read_b128 v[44:47], v222 offset:0
	ds_read_b128 v[48:51], v222 offset:2048
	ds_read_b128 v[12:15], v232 offset:0
	ds_read_b128 v[16:19], v232 offset:2048
	ds_read_b128 v[20:23], v232 offset:4096
	ds_read_b128 v[24:27], v232 offset:6144
	ds_read_b128 v[52:55], v221 offset:0
	ds_read_b128 v[56:59], v221 offset:2048
	ds_read_b128 v[28:31], v231 offset:0
	ds_read_b128 v[32:35], v231 offset:2048
	ds_read_b128 v[36:39], v231 offset:4096
	ds_read_b128 v[40:43], v231 offset:6144
	s_waitcnt lgkmcnt(6)
	v_mfma_f32_16x16x32_bf16 v[60:63], v[12:15], v[44:47], v[60:63]
	v_mfma_f32_16x16x32_bf16 v[64:67], v[12:15], v[48:51], v[64:67]
	v_mfma_f32_16x16x32_bf16 v[68:71], v[16:19], v[44:47], v[68:71]
	v_mfma_f32_16x16x32_bf16 v[72:75], v[16:19], v[48:51], v[72:75]
	v_mfma_f32_16x16x32_bf16 v[76:79], v[20:23], v[44:47], v[76:79]
	v_mfma_f32_16x16x32_bf16 v[80:83], v[20:23], v[48:51], v[80:83]
	v_mfma_f32_16x16x32_bf16 v[84:87], v[24:27], v[44:47], v[84:87]
	v_mfma_f32_16x16x32_bf16 v[88:91], v[24:27], v[48:51], v[88:91]
	s_waitcnt lgkmcnt(0)
	v_mfma_f32_16x16x32_bf16 v[60:63], v[28:31], v[52:55], v[60:63]
	v_mfma_f32_16x16x32_bf16 v[64:67], v[28:31], v[56:59], v[64:67]
	v_mfma_f32_16x16x32_bf16 v[68:71], v[32:35], v[52:55], v[68:71]
	v_mfma_f32_16x16x32_bf16 v[72:75], v[32:35], v[56:59], v[72:75]
	v_mfma_f32_16x16x32_bf16 v[76:79], v[36:39], v[52:55], v[76:79]
	v_mfma_f32_16x16x32_bf16 v[80:83], v[36:39], v[56:59], v[80:83]
	v_mfma_f32_16x16x32_bf16 v[84:87], v[40:43], v[52:55], v[84:87]
	v_mfma_f32_16x16x32_bf16 v[88:91], v[40:43], v[56:59], v[88:91]
	s_nop 3
	global_load_dwordx4 v[92:95], v254, s[16:17] offset:0
	global_load_dwordx4 v[96:99], v254, s[16:17] offset:64
	global_load_dwordx4 v[100:103], v254, s[16:17] offset:128
	global_load_dwordx4 v[104:107], v254, s[16:17] offset:192
	s_cmp_lt_u32 s33, 28
	s_cselect_b32 s43, 0x200, 0
	s_add_u32 s16, s16, s43
	s_addc_u32 s17, s17, 0
	s_add_i32 s33, s33, 1
	s_nop 7
	s_nop 7
	v_cvt_pk_bf16_f32 v140, v60, v61
	v_cvt_pk_bf16_f32 v141, v62, v63
	ds_write_b64 v220, v[140:141] offset:12544
	v_cvt_pk_bf16_f32 v144, v64, v65
	v_cvt_pk_bf16_f32 v145, v66, v67
	ds_write_b64 v220, v[144:145] offset:16640
	s_nop 1
	v_cvt_pk_bf16_f32 v140, v68, v69
	v_cvt_pk_bf16_f32 v141, v70, v71
	ds_write_b64 v219, v[140:141] offset:12544
	v_cvt_pk_bf16_f32 v144, v72, v73
	v_cvt_pk_bf16_f32 v145, v74, v75
	ds_write_b64 v219, v[144:145] offset:16640
	s_nop 1
	v_cvt_pk_bf16_f32 v140, v76, v77
	v_cvt_pk_bf16_f32 v141, v78, v79
	ds_write_b64 v218, v[140:141] offset:12544
	v_cvt_pk_bf16_f32 v144, v80, v81
	v_cvt_pk_bf16_f32 v145, v82, v83
	ds_write_b64 v218, v[144:145] offset:16640
	s_nop 1
	v_cvt_pk_bf16_f32 v140, v84, v85
	v_cvt_pk_bf16_f32 v141, v86, v87
	ds_write_b64 v217, v[140:141] offset:12544
	v_cvt_pk_bf16_f32 v144, v88, v89
	v_cvt_pk_bf16_f32 v145, v90, v91
	ds_write_b64 v217, v[144:145] offset:16640
	s_nop 1
	s_waitcnt vmcnt(8)
	v_pk_mul_f32 v[60:61], v[60:61], v[108:109]
	v_pk_mul_f32 v[62:63], v[62:63], v[110:111]
	v_pk_mul_f32 v[64:65], v[64:65], v[108:109]
	v_pk_mul_f32 v[66:67], v[66:67], v[110:111]
	v_pk_mul_f32 v[68:69], v[68:69], v[112:113]
	v_pk_mul_f32 v[70:71], v[70:71], v[114:115]
	v_pk_mul_f32 v[72:73], v[72:73], v[112:113]
	v_pk_mul_f32 v[74:75], v[74:75], v[114:115]
	v_pk_mul_f32 v[76:77], v[76:77], v[116:117]
	v_pk_mul_f32 v[78:79], v[78:79], v[118:119]
	v_pk_mul_f32 v[80:81], v[80:81], v[116:117]
	v_pk_mul_f32 v[82:83], v[82:83], v[118:119]
	v_pk_mul_f32 v[84:85], v[84:85], v[120:121]
	v_pk_mul_f32 v[86:87], v[86:87], v[122:123]
	v_pk_mul_f32 v[88:89], v[88:89], v[120:121]
	v_pk_mul_f32 v[90:91], v[90:91], v[122:123]
	s_waitcnt lgkmcnt(0)
	s_barrier
	ds_read_b128 v[44:47], v222 offset:12288
	ds_read_b128 v[48:51], v222 offset:14336
	ds_read_b128 v[12:15], v232 offset:40960
	ds_read_b128 v[16:19], v232 offset:43008
	ds_read_b128 v[20:23], v232 offset:45056
	ds_read_b128 v[24:27], v232 offset:47104
	ds_read_b128 v[52:55], v221 offset:12288
	ds_read_b128 v[56:59], v221 offset:14336
	ds_read_b128 v[28:31], v231 offset:40960
	ds_read_b128 v[32:35], v231 offset:43008
	ds_read_b128 v[36:39], v231 offset:45056
	ds_read_b128 v[40:43], v231 offset:47104
	s_waitcnt lgkmcnt(6)
	v_mfma_f32_16x16x32_bf16 v[60:63], v[12:15], v[44:47], v[60:63]
	v_mfma_f32_16x16x32_bf16 v[64:67], v[12:15], v[48:51], v[64:67]
	v_mfma_f32_16x16x32_bf16 v[68:71], v[16:19], v[44:47], v[68:71]
	v_mfma_f32_16x16x32_bf16 v[72:75], v[16:19], v[48:51], v[72:75]
	v_mfma_f32_16x16x32_bf16 v[76:79], v[20:23], v[44:47], v[76:79]
	v_mfma_f32_16x16x32_bf16 v[80:83], v[20:23], v[48:51], v[80:83]
	v_mfma_f32_16x16x32_bf16 v[84:87], v[24:27], v[44:47], v[84:87]
	v_mfma_f32_16x16x32_bf16 v[88:91], v[24:27], v[48:51], v[88:91]
	s_waitcnt lgkmcnt(0)
	v_mfma_f32_16x16x32_bf16 v[60:63], v[28:31], v[52:55], v[60:63]
	v_mfma_f32_16x16x32_bf16 v[64:67], v[28:31], v[56:59], v[64:67]
	v_mfma_f32_16x16x32_bf16 v[68:71], v[32:35], v[52:55], v[68:71]
	v_mfma_f32_16x16x32_bf16 v[72:75], v[32:35], v[56:59], v[72:75]
	v_mfma_f32_16x16x32_bf16 v[76:79], v[36:39], v[52:55], v[76:79]
	v_mfma_f32_16x16x32_bf16 v[80:83], v[36:39], v[56:59], v[80:83]
	v_mfma_f32_16x16x32_bf16 v[84:87], v[40:43], v[52:55], v[84:87]
	v_mfma_f32_16x16x32_bf16 v[88:91], v[40:43], v[56:59], v[88:91]
	s_nop 3
	global_load_dwordx4 v[108:111], v254, s[16:17] offset:0
	global_load_dwordx4 v[112:115], v254, s[16:17] offset:64
	global_load_dwordx4 v[116:119], v254, s[16:17] offset:128
	global_load_dwordx4 v[120:123], v254, s[16:17] offset:192
	s_cmp_lt_u32 s33, 28
	s_cselect_b32 s43, 0x200, 0
	s_add_u32 s16, s16, s43
	s_addc_u32 s17, s17, 0
	s_add_i32 s33, s33, 1
	s_nop 7
	s_nop 7
	v_cvt_pk_bf16_f32 v140, v60, v61
	v_cvt_pk_bf16_f32 v141, v62, v63
	ds_write_b64 v220, v[140:141] offset:0
	v_cvt_pk_bf16_f32 v144, v64, v65
	v_cvt_pk_bf16_f32 v145, v66, v67
	ds_write_b64 v220, v[144:145] offset:4096
	s_nop 1
	v_cvt_pk_bf16_f32 v140, v68, v69
	v_cvt_pk_bf16_f32 v141, v70, v71
	ds_write_b64 v219, v[140:141] offset:0
	v_cvt_pk_bf16_f32 v144, v72, v73
	v_cvt_pk_bf16_f32 v145, v74, v75
	ds_write_b64 v219, v[144:145] offset:4096
	s_nop 1
	v_cvt_pk_bf16_f32 v140, v76, v77
	v_cvt_pk_bf16_f32 v141, v78, v79
	ds_write_b64 v218, v[140:141] offset:0
	v_cvt_pk_bf16_f32 v144, v80, v81
	v_cvt_pk_bf16_f32 v145, v82, v83
	ds_write_b64 v218, v[144:145] offset:4096
	s_nop 1
	v_cvt_pk_bf16_f32 v140, v84, v85
	v_cvt_pk_bf16_f32 v141, v86, v87
	ds_write_b64 v217, v[140:141] offset:0
	v_cvt_pk_bf16_f32 v144, v88, v89
	v_cvt_pk_bf16_f32 v145, v90, v91
	ds_write_b64 v217, v[144:145] offset:4096
	s_nop 1
	s_waitcnt vmcnt(8)
	v_pk_mul_f32 v[60:61], v[60:61], v[124:125]
	v_pk_mul_f32 v[62:63], v[62:63], v[126:127]
	v_pk_mul_f32 v[64:65], v[64:65], v[124:125]
	v_pk_mul_f32 v[66:67], v[66:67], v[126:127]
	v_pk_mul_f32 v[68:69], v[68:69], v[128:129]
	v_pk_mul_f32 v[70:71], v[70:71], v[130:131]
	v_pk_mul_f32 v[72:73], v[72:73], v[128:129]
	v_pk_mul_f32 v[74:75], v[74:75], v[130:131]
	v_pk_mul_f32 v[76:77], v[76:77], v[132:133]
	v_pk_mul_f32 v[78:79], v[78:79], v[134:135]
	v_pk_mul_f32 v[80:81], v[80:81], v[132:133]
	v_pk_mul_f32 v[82:83], v[82:83], v[134:135]
	v_pk_mul_f32 v[84:85], v[84:85], v[136:137]
	v_pk_mul_f32 v[86:87], v[86:87], v[138:139]
	v_pk_mul_f32 v[88:89], v[88:89], v[136:137]
	v_pk_mul_f32 v[90:91], v[90:91], v[138:139]
	s_waitcnt lgkmcnt(0)
	s_barrier
	ds_read_b128 v[44:47], v222 offset:0
	ds_read_b128 v[48:51], v222 offset:2048
	ds_read_b128 v[12:15], v230 offset:0
	ds_read_b128 v[16:19], v230 offset:2048
	ds_read_b128 v[20:23], v230 offset:4096
	ds_read_b128 v[24:27], v230 offset:6144
	ds_read_b128 v[52:55], v221 offset:0
	ds_read_b128 v[56:59], v221 offset:2048
	ds_read_b128 v[28:31], v229 offset:0
	ds_read_b128 v[32:35], v229 offset:2048
	ds_read_b128 v[36:39], v229 offset:4096
	ds_read_b128 v[40:43], v229 offset:6144
	s_waitcnt lgkmcnt(6)
	v_mfma_f32_16x16x32_bf16 v[60:63], v[12:15], v[44:47], v[60:63]
	v_mfma_f32_16x16x32_bf16 v[64:67], v[12:15], v[48:51], v[64:67]
	v_mfma_f32_16x16x32_bf16 v[68:71], v[16:19], v[44:47], v[68:71]
	v_mfma_f32_16x16x32_bf16 v[72:75], v[16:19], v[48:51], v[72:75]
	v_mfma_f32_16x16x32_bf16 v[76:79], v[20:23], v[44:47], v[76:79]
	v_mfma_f32_16x16x32_bf16 v[80:83], v[20:23], v[48:51], v[80:83]
	v_mfma_f32_16x16x32_bf16 v[84:87], v[24:27], v[44:47], v[84:87]
	v_mfma_f32_16x16x32_bf16 v[88:91], v[24:27], v[48:51], v[88:91]
	s_waitcnt lgkmcnt(0)
	v_mfma_f32_16x16x32_bf16 v[60:63], v[28:31], v[52:55], v[60:63]
	v_mfma_f32_16x16x32_bf16 v[64:67], v[28:31], v[56:59], v[64:67]
	v_mfma_f32_16x16x32_bf16 v[68:71], v[32:35], v[52:55], v[68:71]
	v_mfma_f32_16x16x32_bf16 v[72:75], v[32:35], v[56:59], v[72:75]
	v_mfma_f32_16x16x32_bf16 v[76:79], v[36:39], v[52:55], v[76:79]
	v_mfma_f32_16x16x32_bf16 v[80:83], v[36:39], v[56:59], v[80:83]
	v_mfma_f32_16x16x32_bf16 v[84:87], v[40:43], v[52:55], v[84:87]
	v_mfma_f32_16x16x32_bf16 v[88:91], v[40:43], v[56:59], v[88:91]
	s_nop 3
	global_load_dwordx4 v[124:127], v254, s[16:17] offset:0
	global_load_dwordx4 v[128:131], v254, s[16:17] offset:64
	global_load_dwordx4 v[132:135], v254, s[16:17] offset:128
	global_load_dwordx4 v[136:139], v254, s[16:17] offset:192
	s_cmp_lt_u32 s33, 28
	s_cselect_b32 s43, 0x200, 0
	s_add_u32 s16, s16, s43
	s_addc_u32 s17, s17, 0
	s_add_i32 s33, s33, 1
	s_nop 7
	s_nop 7
	v_cvt_pk_bf16_f32 v140, v60, v61
	v_cvt_pk_bf16_f32 v141, v62, v63
	ds_write_b64 v220, v[140:141] offset:12544
	v_cvt_pk_bf16_f32 v144, v64, v65
	v_cvt_pk_bf16_f32 v145, v66, v67
	ds_write_b64 v220, v[144:145] offset:16640
	s_nop 1
	v_cvt_pk_bf16_f32 v140, v68, v69
	v_cvt_pk_bf16_f32 v141, v70, v71
	ds_write_b64 v219, v[140:141] offset:12544
	v_cvt_pk_bf16_f32 v144, v72, v73
	v_cvt_pk_bf16_f32 v145, v74, v75
	ds_write_b64 v219, v[144:145] offset:16640
	s_nop 1
	v_cvt_pk_bf16_f32 v140, v76, v77
	v_cvt_pk_bf16_f32 v141, v78, v79
	ds_write_b64 v218, v[140:141] offset:12544
	v_cvt_pk_bf16_f32 v144, v80, v81
	v_cvt_pk_bf16_f32 v145, v82, v83
	ds_write_b64 v218, v[144:145] offset:16640
	s_nop 1
	v_cvt_pk_bf16_f32 v140, v84, v85
	v_cvt_pk_bf16_f32 v141, v86, v87
	ds_write_b64 v217, v[140:141] offset:12544
	v_cvt_pk_bf16_f32 v144, v88, v89
	v_cvt_pk_bf16_f32 v145, v90, v91
	ds_write_b64 v217, v[144:145] offset:16640
	s_nop 1
	s_waitcnt vmcnt(8)
	v_pk_mul_f32 v[60:61], v[60:61], v[92:93]
	v_pk_mul_f32 v[62:63], v[62:63], v[94:95]
	v_pk_mul_f32 v[64:65], v[64:65], v[92:93]
	v_pk_mul_f32 v[66:67], v[66:67], v[94:95]
	v_pk_mul_f32 v[68:69], v[68:69], v[96:97]
	v_pk_mul_f32 v[70:71], v[70:71], v[98:99]
	v_pk_mul_f32 v[72:73], v[72:73], v[96:97]
	v_pk_mul_f32 v[74:75], v[74:75], v[98:99]
	v_pk_mul_f32 v[76:77], v[76:77], v[100:101]
	v_pk_mul_f32 v[78:79], v[78:79], v[102:103]
	v_pk_mul_f32 v[80:81], v[80:81], v[100:101]
	v_pk_mul_f32 v[82:83], v[82:83], v[102:103]
	v_pk_mul_f32 v[84:85], v[84:85], v[104:105]
	v_pk_mul_f32 v[86:87], v[86:87], v[106:107]
	v_pk_mul_f32 v[88:89], v[88:89], v[104:105]
	v_pk_mul_f32 v[90:91], v[90:91], v[106:107]
	s_waitcnt lgkmcnt(0)
	s_barrier
	ds_read_b128 v[44:47], v222 offset:12288
	ds_read_b128 v[48:51], v222 offset:14336
	ds_read_b128 v[12:15], v232 offset:0
	ds_read_b128 v[16:19], v232 offset:2048
	ds_read_b128 v[20:23], v232 offset:4096
	ds_read_b128 v[24:27], v232 offset:6144
	ds_read_b128 v[52:55], v221 offset:12288
	ds_read_b128 v[56:59], v221 offset:14336
	ds_read_b128 v[28:31], v231 offset:0
	ds_read_b128 v[32:35], v231 offset:2048
	ds_read_b128 v[36:39], v231 offset:4096
	ds_read_b128 v[40:43], v231 offset:6144
	s_waitcnt lgkmcnt(6)
	v_mfma_f32_16x16x32_bf16 v[60:63], v[12:15], v[44:47], v[60:63]
	v_mfma_f32_16x16x32_bf16 v[64:67], v[12:15], v[48:51], v[64:67]
	v_mfma_f32_16x16x32_bf16 v[68:71], v[16:19], v[44:47], v[68:71]
	v_mfma_f32_16x16x32_bf16 v[72:75], v[16:19], v[48:51], v[72:75]
	v_mfma_f32_16x16x32_bf16 v[76:79], v[20:23], v[44:47], v[76:79]
	v_mfma_f32_16x16x32_bf16 v[80:83], v[20:23], v[48:51], v[80:83]
	v_mfma_f32_16x16x32_bf16 v[84:87], v[24:27], v[44:47], v[84:87]
	v_mfma_f32_16x16x32_bf16 v[88:91], v[24:27], v[48:51], v[88:91]
	s_waitcnt lgkmcnt(0)
	v_mfma_f32_16x16x32_bf16 v[60:63], v[28:31], v[52:55], v[60:63]
	v_mfma_f32_16x16x32_bf16 v[64:67], v[28:31], v[56:59], v[64:67]
	v_mfma_f32_16x16x32_bf16 v[68:71], v[32:35], v[52:55], v[68:71]
	v_mfma_f32_16x16x32_bf16 v[72:75], v[32:35], v[56:59], v[72:75]
	v_mfma_f32_16x16x32_bf16 v[76:79], v[36:39], v[52:55], v[76:79]
	v_mfma_f32_16x16x32_bf16 v[80:83], v[36:39], v[56:59], v[80:83]
	v_mfma_f32_16x16x32_bf16 v[84:87], v[40:43], v[52:55], v[84:87]
	v_mfma_f32_16x16x32_bf16 v[88:91], v[40:43], v[56:59], v[88:91]
	s_nop 3
	global_load_dwordx4 v[92:95], v254, s[16:17] offset:0
	global_load_dwordx4 v[96:99], v254, s[16:17] offset:64
	global_load_dwordx4 v[100:103], v254, s[16:17] offset:128
	global_load_dwordx4 v[104:107], v254, s[16:17] offset:192
	s_cmp_lt_u32 s33, 28
	s_cselect_b32 s43, 0x200, 0
	s_add_u32 s16, s16, s43
	s_addc_u32 s17, s17, 0
	s_add_i32 s33, s33, 1
	s_nop 7
	s_nop 7
	v_cvt_pk_bf16_f32 v140, v60, v61
	v_cvt_pk_bf16_f32 v141, v62, v63
	ds_write_b64 v220, v[140:141] offset:0
	v_cvt_pk_bf16_f32 v144, v64, v65
	v_cvt_pk_bf16_f32 v145, v66, v67
	ds_write_b64 v220, v[144:145] offset:4096
	s_nop 1
	v_cvt_pk_bf16_f32 v140, v68, v69
	v_cvt_pk_bf16_f32 v141, v70, v71
	ds_write_b64 v219, v[140:141] offset:0
	v_cvt_pk_bf16_f32 v144, v72, v73
	v_cvt_pk_bf16_f32 v145, v74, v75
	ds_write_b64 v219, v[144:145] offset:4096
	s_nop 1
	v_cvt_pk_bf16_f32 v140, v76, v77
	v_cvt_pk_bf16_f32 v141, v78, v79
	ds_write_b64 v218, v[140:141] offset:0
	v_cvt_pk_bf16_f32 v144, v80, v81
	v_cvt_pk_bf16_f32 v145, v82, v83
	ds_write_b64 v218, v[144:145] offset:4096
	s_nop 1
	v_cvt_pk_bf16_f32 v140, v84, v85
	v_cvt_pk_bf16_f32 v141, v86, v87
	ds_write_b64 v217, v[140:141] offset:0
	v_cvt_pk_bf16_f32 v144, v88, v89
	v_cvt_pk_bf16_f32 v145, v90, v91
	ds_write_b64 v217, v[144:145] offset:4096
	s_nop 1
	s_waitcnt vmcnt(8)
	v_pk_mul_f32 v[60:61], v[60:61], v[108:109]
	v_pk_mul_f32 v[62:63], v[62:63], v[110:111]
	v_pk_mul_f32 v[64:65], v[64:65], v[108:109]
	v_pk_mul_f32 v[66:67], v[66:67], v[110:111]
	v_pk_mul_f32 v[68:69], v[68:69], v[112:113]
	v_pk_mul_f32 v[70:71], v[70:71], v[114:115]
	v_pk_mul_f32 v[72:73], v[72:73], v[112:113]
	v_pk_mul_f32 v[74:75], v[74:75], v[114:115]
	v_pk_mul_f32 v[76:77], v[76:77], v[116:117]
	v_pk_mul_f32 v[78:79], v[78:79], v[118:119]
	v_pk_mul_f32 v[80:81], v[80:81], v[116:117]
	v_pk_mul_f32 v[82:83], v[82:83], v[118:119]
	v_pk_mul_f32 v[84:85], v[84:85], v[120:121]
	v_pk_mul_f32 v[86:87], v[86:87], v[122:123]
	v_pk_mul_f32 v[88:89], v[88:89], v[120:121]
	v_pk_mul_f32 v[90:91], v[90:91], v[122:123]
	s_waitcnt lgkmcnt(0)
	s_barrier
	ds_read_b128 v[44:47], v222 offset:0
	ds_read_b128 v[48:51], v222 offset:2048
	ds_read_b128 v[12:15], v232 offset:40960
	ds_read_b128 v[16:19], v232 offset:43008
	ds_read_b128 v[20:23], v232 offset:45056
	ds_read_b128 v[24:27], v232 offset:47104
	ds_read_b128 v[52:55], v221 offset:0
	ds_read_b128 v[56:59], v221 offset:2048
	ds_read_b128 v[28:31], v231 offset:40960
	ds_read_b128 v[32:35], v231 offset:43008
	ds_read_b128 v[36:39], v231 offset:45056
	ds_read_b128 v[40:43], v231 offset:47104
	s_waitcnt lgkmcnt(6)
	v_mfma_f32_16x16x32_bf16 v[60:63], v[12:15], v[44:47], v[60:63]
	v_mfma_f32_16x16x32_bf16 v[64:67], v[12:15], v[48:51], v[64:67]
	v_mfma_f32_16x16x32_bf16 v[68:71], v[16:19], v[44:47], v[68:71]
	v_mfma_f32_16x16x32_bf16 v[72:75], v[16:19], v[48:51], v[72:75]
	v_mfma_f32_16x16x32_bf16 v[76:79], v[20:23], v[44:47], v[76:79]
	v_mfma_f32_16x16x32_bf16 v[80:83], v[20:23], v[48:51], v[80:83]
	v_mfma_f32_16x16x32_bf16 v[84:87], v[24:27], v[44:47], v[84:87]
	v_mfma_f32_16x16x32_bf16 v[88:91], v[24:27], v[48:51], v[88:91]
	s_waitcnt lgkmcnt(0)
	v_mfma_f32_16x16x32_bf16 v[60:63], v[28:31], v[52:55], v[60:63]
	v_mfma_f32_16x16x32_bf16 v[64:67], v[28:31], v[56:59], v[64:67]
	v_mfma_f32_16x16x32_bf16 v[68:71], v[32:35], v[52:55], v[68:71]
	v_mfma_f32_16x16x32_bf16 v[72:75], v[32:35], v[56:59], v[72:75]
	v_mfma_f32_16x16x32_bf16 v[76:79], v[36:39], v[52:55], v[76:79]
	v_mfma_f32_16x16x32_bf16 v[80:83], v[36:39], v[56:59], v[80:83]
	v_mfma_f32_16x16x32_bf16 v[84:87], v[40:43], v[52:55], v[84:87]
	v_mfma_f32_16x16x32_bf16 v[88:91], v[40:43], v[56:59], v[88:91]
	s_nop 3
	global_load_dwordx4 v[108:111], v254, s[16:17] offset:0
	global_load_dwordx4 v[112:115], v254, s[16:17] offset:64
	global_load_dwordx4 v[116:119], v254, s[16:17] offset:128
	global_load_dwordx4 v[120:123], v254, s[16:17] offset:192
	s_cmp_lt_u32 s33, 28
	s_cselect_b32 s43, 0x200, 0
	s_add_u32 s16, s16, s43
	s_addc_u32 s17, s17, 0
	s_add_i32 s33, s33, 1
	s_nop 7
	s_nop 7
	v_cvt_pk_bf16_f32 v140, v60, v61
	v_cvt_pk_bf16_f32 v141, v62, v63
	ds_write_b64 v220, v[140:141] offset:12544
	v_cvt_pk_bf16_f32 v144, v64, v65
	v_cvt_pk_bf16_f32 v145, v66, v67
	ds_write_b64 v220, v[144:145] offset:16640
	s_nop 1
	v_cvt_pk_bf16_f32 v140, v68, v69
	v_cvt_pk_bf16_f32 v141, v70, v71
	ds_write_b64 v219, v[140:141] offset:12544
	v_cvt_pk_bf16_f32 v144, v72, v73
	v_cvt_pk_bf16_f32 v145, v74, v75
	ds_write_b64 v219, v[144:145] offset:16640
	s_nop 1
	v_cvt_pk_bf16_f32 v140, v76, v77
	v_cvt_pk_bf16_f32 v141, v78, v79
	ds_write_b64 v218, v[140:141] offset:12544
	v_cvt_pk_bf16_f32 v144, v80, v81
	v_cvt_pk_bf16_f32 v145, v82, v83
	ds_write_b64 v218, v[144:145] offset:16640
	s_nop 1
	v_cvt_pk_bf16_f32 v140, v84, v85
	v_cvt_pk_bf16_f32 v141, v86, v87
	ds_write_b64 v217, v[140:141] offset:12544
	v_cvt_pk_bf16_f32 v144, v88, v89
	v_cvt_pk_bf16_f32 v145, v90, v91
	ds_write_b64 v217, v[144:145] offset:16640
	s_nop 1
	s_waitcnt vmcnt(8)
	v_pk_mul_f32 v[60:61], v[60:61], v[124:125]
	v_pk_mul_f32 v[62:63], v[62:63], v[126:127]
	v_pk_mul_f32 v[64:65], v[64:65], v[124:125]
	v_pk_mul_f32 v[66:67], v[66:67], v[126:127]
	v_pk_mul_f32 v[68:69], v[68:69], v[128:129]
	v_pk_mul_f32 v[70:71], v[70:71], v[130:131]
	v_pk_mul_f32 v[72:73], v[72:73], v[128:129]
	v_pk_mul_f32 v[74:75], v[74:75], v[130:131]
	v_pk_mul_f32 v[76:77], v[76:77], v[132:133]
	v_pk_mul_f32 v[78:79], v[78:79], v[134:135]
	v_pk_mul_f32 v[80:81], v[80:81], v[132:133]
	v_pk_mul_f32 v[82:83], v[82:83], v[134:135]
	v_pk_mul_f32 v[84:85], v[84:85], v[136:137]
	v_pk_mul_f32 v[86:87], v[86:87], v[138:139]
	v_pk_mul_f32 v[88:89], v[88:89], v[136:137]
	v_pk_mul_f32 v[90:91], v[90:91], v[138:139]
	s_waitcnt lgkmcnt(0)
	s_barrier
	ds_read_b128 v[44:47], v222 offset:12288
	ds_read_b128 v[48:51], v222 offset:14336
	ds_read_b128 v[12:15], v230 offset:0
	ds_read_b128 v[16:19], v230 offset:2048
	ds_read_b128 v[20:23], v230 offset:4096
	ds_read_b128 v[24:27], v230 offset:6144
	ds_read_b128 v[52:55], v221 offset:12288
	ds_read_b128 v[56:59], v221 offset:14336
	ds_read_b128 v[28:31], v229 offset:0
	ds_read_b128 v[32:35], v229 offset:2048
	ds_read_b128 v[36:39], v229 offset:4096
	ds_read_b128 v[40:43], v229 offset:6144
	s_waitcnt lgkmcnt(6)
	v_mfma_f32_16x16x32_bf16 v[60:63], v[12:15], v[44:47], v[60:63]
	v_mfma_f32_16x16x32_bf16 v[64:67], v[12:15], v[48:51], v[64:67]
	v_mfma_f32_16x16x32_bf16 v[68:71], v[16:19], v[44:47], v[68:71]
	v_mfma_f32_16x16x32_bf16 v[72:75], v[16:19], v[48:51], v[72:75]
	v_mfma_f32_16x16x32_bf16 v[76:79], v[20:23], v[44:47], v[76:79]
	v_mfma_f32_16x16x32_bf16 v[80:83], v[20:23], v[48:51], v[80:83]
	v_mfma_f32_16x16x32_bf16 v[84:87], v[24:27], v[44:47], v[84:87]
	v_mfma_f32_16x16x32_bf16 v[88:91], v[24:27], v[48:51], v[88:91]
	s_waitcnt lgkmcnt(0)
	v_mfma_f32_16x16x32_bf16 v[60:63], v[28:31], v[52:55], v[60:63]
	v_mfma_f32_16x16x32_bf16 v[64:67], v[28:31], v[56:59], v[64:67]
	v_mfma_f32_16x16x32_bf16 v[68:71], v[32:35], v[52:55], v[68:71]
	v_mfma_f32_16x16x32_bf16 v[72:75], v[32:35], v[56:59], v[72:75]
	v_mfma_f32_16x16x32_bf16 v[76:79], v[36:39], v[52:55], v[76:79]
	v_mfma_f32_16x16x32_bf16 v[80:83], v[36:39], v[56:59], v[80:83]
	v_mfma_f32_16x16x32_bf16 v[84:87], v[40:43], v[52:55], v[84:87]
	v_mfma_f32_16x16x32_bf16 v[88:91], v[40:43], v[56:59], v[88:91]
	s_nop 3
	global_load_dwordx4 v[124:127], v254, s[16:17] offset:0
	global_load_dwordx4 v[128:131], v254, s[16:17] offset:64
	global_load_dwordx4 v[132:135], v254, s[16:17] offset:128
	global_load_dwordx4 v[136:139], v254, s[16:17] offset:192
	s_cmp_lt_u32 s33, 28
	s_cselect_b32 s43, 0x200, 0
	s_add_u32 s16, s16, s43
	s_addc_u32 s17, s17, 0
	s_add_i32 s33, s33, 1
	s_nop 7
	s_nop 7
	v_cvt_pk_bf16_f32 v140, v60, v61
	v_cvt_pk_bf16_f32 v141, v62, v63
	ds_write_b64 v220, v[140:141] offset:0
	v_cvt_pk_bf16_f32 v144, v64, v65
	v_cvt_pk_bf16_f32 v145, v66, v67
	ds_write_b64 v220, v[144:145] offset:4096
	s_nop 1
	v_cvt_pk_bf16_f32 v140, v68, v69
	v_cvt_pk_bf16_f32 v141, v70, v71
	ds_write_b64 v219, v[140:141] offset:0
	v_cvt_pk_bf16_f32 v144, v72, v73
	v_cvt_pk_bf16_f32 v145, v74, v75
	ds_write_b64 v219, v[144:145] offset:4096
	s_nop 1
	v_cvt_pk_bf16_f32 v140, v76, v77
	v_cvt_pk_bf16_f32 v141, v78, v79
	ds_write_b64 v218, v[140:141] offset:0
	v_cvt_pk_bf16_f32 v144, v80, v81
	v_cvt_pk_bf16_f32 v145, v82, v83
	ds_write_b64 v218, v[144:145] offset:4096
	s_nop 1
	v_cvt_pk_bf16_f32 v140, v84, v85
	v_cvt_pk_bf16_f32 v141, v86, v87
	ds_write_b64 v217, v[140:141] offset:0
	v_cvt_pk_bf16_f32 v144, v88, v89
	v_cvt_pk_bf16_f32 v145, v90, v91
	ds_write_b64 v217, v[144:145] offset:4096
	s_nop 1
	s_waitcnt vmcnt(8)
	v_pk_mul_f32 v[60:61], v[60:61], v[92:93]
	v_pk_mul_f32 v[62:63], v[62:63], v[94:95]
	v_pk_mul_f32 v[64:65], v[64:65], v[92:93]
	v_pk_mul_f32 v[66:67], v[66:67], v[94:95]
	v_pk_mul_f32 v[68:69], v[68:69], v[96:97]
	v_pk_mul_f32 v[70:71], v[70:71], v[98:99]
	v_pk_mul_f32 v[72:73], v[72:73], v[96:97]
	v_pk_mul_f32 v[74:75], v[74:75], v[98:99]
	v_pk_mul_f32 v[76:77], v[76:77], v[100:101]
	v_pk_mul_f32 v[78:79], v[78:79], v[102:103]
	v_pk_mul_f32 v[80:81], v[80:81], v[100:101]
	v_pk_mul_f32 v[82:83], v[82:83], v[102:103]
	v_pk_mul_f32 v[84:85], v[84:85], v[104:105]
	v_pk_mul_f32 v[86:87], v[86:87], v[106:107]
	v_pk_mul_f32 v[88:89], v[88:89], v[104:105]
	v_pk_mul_f32 v[90:91], v[90:91], v[106:107]
	s_waitcnt lgkmcnt(0)
	s_barrier
	s_cmp_lt_u32 s33, 30
	s_cbranch_scc1 .Lp3S_loop
	ds_read_b128 v[44:47], v222 offset:0
	ds_read_b128 v[48:51], v222 offset:2048
	ds_read_b128 v[12:15], v232 offset:0
	ds_read_b128 v[16:19], v232 offset:2048
	ds_read_b128 v[20:23], v232 offset:4096
	ds_read_b128 v[24:27], v232 offset:6144
	ds_read_b128 v[52:55], v221 offset:0
	ds_read_b128 v[56:59], v221 offset:2048
	ds_read_b128 v[28:31], v231 offset:0
	ds_read_b128 v[32:35], v231 offset:2048
	ds_read_b128 v[36:39], v231 offset:4096
	ds_read_b128 v[40:43], v231 offset:6144
	s_waitcnt lgkmcnt(6)
	v_mfma_f32_16x16x32_bf16 v[60:63], v[12:15], v[44:47], v[60:63]
	v_mfma_f32_16x16x32_bf16 v[64:67], v[12:15], v[48:51], v[64:67]
	v_mfma_f32_16x16x32_bf16 v[68:71], v[16:19], v[44:47], v[68:71]
	v_mfma_f32_16x16x32_bf16 v[72:75], v[16:19], v[48:51], v[72:75]
	v_mfma_f32_16x16x32_bf16 v[76:79], v[20:23], v[44:47], v[76:79]
	v_mfma_f32_16x16x32_bf16 v[80:83], v[20:23], v[48:51], v[80:83]
	v_mfma_f32_16x16x32_bf16 v[84:87], v[24:27], v[44:47], v[84:87]
	v_mfma_f32_16x16x32_bf16 v[88:91], v[24:27], v[48:51], v[88:91]
	s_waitcnt lgkmcnt(0)
	v_mfma_f32_16x16x32_bf16 v[60:63], v[28:31], v[52:55], v[60:63]
	v_mfma_f32_16x16x32_bf16 v[64:67], v[28:31], v[56:59], v[64:67]
	v_mfma_f32_16x16x32_bf16 v[68:71], v[32:35], v[52:55], v[68:71]
	v_mfma_f32_16x16x32_bf16 v[72:75], v[32:35], v[56:59], v[72:75]
	v_mfma_f32_16x16x32_bf16 v[76:79], v[36:39], v[52:55], v[76:79]
	v_mfma_f32_16x16x32_bf16 v[80:83], v[36:39], v[56:59], v[80:83]
	v_mfma_f32_16x16x32_bf16 v[84:87], v[40:43], v[52:55], v[84:87]
	v_mfma_f32_16x16x32_bf16 v[88:91], v[40:43], v[56:59], v[88:91]
	s_nop 3
	global_load_dwordx4 v[92:95], v254, s[16:17] offset:0
	global_load_dwordx4 v[96:99], v254, s[16:17] offset:64
	global_load_dwordx4 v[100:103], v254, s[16:17] offset:128
	global_load_dwordx4 v[104:107], v254, s[16:17] offset:192
	s_cmp_lt_u32 s33, 28
	s_cselect_b32 s43, 0x200, 0
	s_add_u32 s16, s16, s43
	s_addc_u32 s17, s17, 0
	s_add_i32 s33, s33, 1
	s_nop 7
	s_nop 7
	v_cvt_pk_bf16_f32 v140, v60, v61
	v_cvt_pk_bf16_f32 v141, v62, v63
	ds_write_b64 v220, v[140:141] offset:12544
	v_cvt_pk_bf16_f32 v144, v64, v65
	v_cvt_pk_bf16_f32 v145, v66, v67
	ds_write_b64 v220, v[144:145] offset:16640
	s_nop 1
	v_cvt_pk_bf16_f32 v140, v68, v69
	v_cvt_pk_bf16_f32 v141, v70, v71
	ds_write_b64 v219, v[140:141] offset:12544
	v_cvt_pk_bf16_f32 v144, v72, v73
	v_cvt_pk_bf16_f32 v145, v74, v75
	ds_write_b64 v219, v[144:145] offset:16640
	s_nop 1
	v_cvt_pk_bf16_f32 v140, v76, v77
	v_cvt_pk_bf16_f32 v141, v78, v79
	ds_write_b64 v218, v[140:141] offset:12544
	v_cvt_pk_bf16_f32 v144, v80, v81
	v_cvt_pk_bf16_f32 v145, v82, v83
	ds_write_b64 v218, v[144:145] offset:16640
	s_nop 1
	v_cvt_pk_bf16_f32 v140, v84, v85
	v_cvt_pk_bf16_f32 v141, v86, v87
	ds_write_b64 v217, v[140:141] offset:12544
	v_cvt_pk_bf16_f32 v144, v88, v89
	v_cvt_pk_bf16_f32 v145, v90, v91
	ds_write_b64 v217, v[144:145] offset:16640
	s_nop 1
	s_waitcnt vmcnt(8)
	v_pk_mul_f32 v[60:61], v[60:61], v[108:109]
	v_pk_mul_f32 v[62:63], v[62:63], v[110:111]
	v_pk_mul_f32 v[64:65], v[64:65], v[108:109]
	v_pk_mul_f32 v[66:67], v[66:67], v[110:111]
	v_pk_mul_f32 v[68:69], v[68:69], v[112:113]
	v_pk_mul_f32 v[70:71], v[70:71], v[114:115]
	v_pk_mul_f32 v[72:73], v[72:73], v[112:113]
	v_pk_mul_f32 v[74:75], v[74:75], v[114:115]
	v_pk_mul_f32 v[76:77], v[76:77], v[116:117]
	v_pk_mul_f32 v[78:79], v[78:79], v[118:119]
	v_pk_mul_f32 v[80:81], v[80:81], v[116:117]
	v_pk_mul_f32 v[82:83], v[82:83], v[118:119]
	v_pk_mul_f32 v[84:85], v[84:85], v[120:121]
	v_pk_mul_f32 v[86:87], v[86:87], v[122:123]
	v_pk_mul_f32 v[88:89], v[88:89], v[120:121]
	v_pk_mul_f32 v[90:91], v[90:91], v[122:123]
	s_waitcnt lgkmcnt(0)
	s_barrier
; __device__ __forceinline__ void gla_scan_item(const Ctx& C, int item, LAS unsigned char* lds, int tid) {
;     ...
;     SCAN_LOAD(A, 0); SCAN_LOAD(B, 1);
; #pragma unroll
;     for (int n = 0; n < 32; n += 2) { SCAN_STEP(A, n); SCAN_STEP(B, n + 1); }
;     ...
;     float* So = C.out + OUT_GLAP + ((size_t)bh * 128 + wave * 16 + quad * 4) * 256 + sl * 32 + l15;
; #pragma unroll
;     for (int v2 = 0; v2 < 2; ++v2)
; #pragma unroll
;         for (int j = 0; j < 4; ++j) So[(size_t)j * 256 + v2 * 16] = S[v2][j];
;     __syncthreads();
	ds_read_b128 v[44:47], v222 offset:12288
	ds_read_b128 v[48:51], v222 offset:14336
	ds_read_b128 v[12:15], v232 offset:40960
	ds_read_b128 v[16:19], v232 offset:43008
	ds_read_b128 v[20:23], v232 offset:45056
	ds_read_b128 v[24:27], v232 offset:47104
	ds_read_b128 v[52:55], v221 offset:12288
	ds_read_b128 v[56:59], v221 offset:14336
	ds_read_b128 v[28:31], v231 offset:40960
	ds_read_b128 v[32:35], v231 offset:43008
	ds_read_b128 v[36:39], v231 offset:45056
	ds_read_b128 v[40:43], v231 offset:47104
	s_waitcnt lgkmcnt(6)
	v_mfma_f32_16x16x32_bf16 v[60:63], v[12:15], v[44:47], v[60:63]
	v_mfma_f32_16x16x32_bf16 v[64:67], v[12:15], v[48:51], v[64:67]
	v_mfma_f32_16x16x32_bf16 v[68:71], v[16:19], v[44:47], v[68:71]
	v_mfma_f32_16x16x32_bf16 v[72:75], v[16:19], v[48:51], v[72:75]
	v_mfma_f32_16x16x32_bf16 v[76:79], v[20:23], v[44:47], v[76:79]
	v_mfma_f32_16x16x32_bf16 v[80:83], v[20:23], v[48:51], v[80:83]
	v_mfma_f32_16x16x32_bf16 v[84:87], v[24:27], v[44:47], v[84:87]
	v_mfma_f32_16x16x32_bf16 v[88:91], v[24:27], v[48:51], v[88:91]
	s_waitcnt lgkmcnt(0)
	v_mfma_f32_16x16x32_bf16 v[60:63], v[28:31], v[52:55], v[60:63]
	v_mfma_f32_16x16x32_bf16 v[64:67], v[28:31], v[56:59], v[64:67]
	v_mfma_f32_16x16x32_bf16 v[68:71], v[32:35], v[52:55], v[68:71]
	v_mfma_f32_16x16x32_bf16 v[72:75], v[32:35], v[56:59], v[72:75]
	v_mfma_f32_16x16x32_bf16 v[76:79], v[36:39], v[52:55], v[76:79]
	v_mfma_f32_16x16x32_bf16 v[80:83], v[36:39], v[56:59], v[80:83]
	v_mfma_f32_16x16x32_bf16 v[84:87], v[40:43], v[52:55], v[84:87]
	v_mfma_f32_16x16x32_bf16 v[88:91], v[40:43], v[56:59], v[88:91]
	s_nop 3
	global_load_dwordx4 v[108:111], v254, s[16:17] offset:0
	global_load_dwordx4 v[112:115], v254, s[16:17] offset:64
	global_load_dwordx4 v[116:119], v254, s[16:17] offset:128
	global_load_dwordx4 v[120:123], v254, s[16:17] offset:192
	s_cmp_lt_u32 s33, 28
	s_cselect_b32 s43, 0x200, 0
	s_add_u32 s16, s16, s43
	s_addc_u32 s17, s17, 0
	s_add_i32 s33, s33, 1
	s_nop 7
	s_nop 7
	v_cvt_pk_bf16_f32 v140, v60, v61
	v_cvt_pk_bf16_f32 v141, v62, v63
	ds_write_b64 v220, v[140:141] offset:0
	v_cvt_pk_bf16_f32 v144, v64, v65
	v_cvt_pk_bf16_f32 v145, v66, v67
	ds_write_b64 v220, v[144:145] offset:4096
	s_nop 1
	v_cvt_pk_bf16_f32 v140, v68, v69
	v_cvt_pk_bf16_f32 v141, v70, v71
	ds_write_b64 v219, v[140:141] offset:0
	v_cvt_pk_bf16_f32 v144, v72, v73
	v_cvt_pk_bf16_f32 v145, v74, v75
	ds_write_b64 v219, v[144:145] offset:4096
	s_nop 1
	v_cvt_pk_bf16_f32 v140, v76, v77
	v_cvt_pk_bf16_f32 v141, v78, v79
	ds_write_b64 v218, v[140:141] offset:0
	v_cvt_pk_bf16_f32 v144, v80, v81
	v_cvt_pk_bf16_f32 v145, v82, v83
	ds_write_b64 v218, v[144:145] offset:4096
	s_nop 1
	v_cvt_pk_bf16_f32 v140, v84, v85
	v_cvt_pk_bf16_f32 v141, v86, v87
	ds_write_b64 v217, v[140:141] offset:0
	v_cvt_pk_bf16_f32 v144, v88, v89
	v_cvt_pk_bf16_f32 v145, v90, v91
	ds_write_b64 v217, v[144:145] offset:4096
	s_nop 1
	s_waitcnt lgkmcnt(0)
	s_barrier
	s_nop 7
	global_store_dword v250, v60, s[34:35] offset:0
	global_store_dword v250, v61, s[34:35] offset:1024
	global_store_dword v250, v62, s[34:35] offset:2048
	global_store_dword v250, v63, s[34:35] offset:3072
	global_store_dword v250, v64, s[34:35] offset:64
	global_store_dword v250, v65, s[34:35] offset:1088
	global_store_dword v250, v66, s[34:35] offset:2112
	global_store_dword v250, v67, s[34:35] offset:3136
	global_store_dword v249, v68, s[34:35] offset:0
	global_store_dword v249, v69, s[34:35] offset:1024
	global_store_dword v249, v70, s[34:35] offset:2048
	global_store_dword v249, v71, s[34:35] offset:3072
	global_store_dword v249, v72, s[34:35] offset:64
	global_store_dword v249, v73, s[34:35] offset:1088
	global_store_dword v249, v74, s[34:35] offset:2112
	global_store_dword v249, v75, s[34:35] offset:3136
	global_store_dword v248, v76, s[34:35] offset:0
	global_store_dword v248, v77, s[34:35] offset:1024
	global_store_dword v248, v78, s[34:35] offset:2048
	global_store_dword v248, v79, s[34:35] offset:3072
	global_store_dword v248, v80, s[34:35] offset:64
	global_store_dword v248, v81, s[34:35] offset:1088
	global_store_dword v248, v82, s[34:35] offset:2112
	global_store_dword v248, v83, s[34:35] offset:3136
	global_store_dword v247, v84, s[34:35] offset:0
	global_store_dword v247, v85, s[34:35] offset:1024
	global_store_dword v247, v86, s[34:35] offset:2048
	global_store_dword v247, v87, s[34:35] offset:3072
	global_store_dword v247, v88, s[34:35] offset:64
	global_store_dword v247, v89, s[34:35] offset:1088
	global_store_dword v247, v90, s[34:35] offset:2112
	global_store_dword v247, v91, s[34:35] offset:3136
	s_waitcnt vmcnt(0) lgkmcnt(0)
	s_barrier
	s_add_i32 s3, s3, s42
	s_cmpk_lt_i32 s3, 0x100
	s_cbranch_scc1 .Lp3S_item
	s_branch .Lp3_done

; #define LAS __attribute__((address_space(3)))
; __device__ __forceinline__ void gla_scan_item(const Ctx& C, int item, LAS unsigned char* lds, int tid) {
;     const int jx = item >> 3, bh = (item & 7) * 4 + (jx >> 3), sl = jx & 7, b = bh >> 2, h = bh & 3;
;     LAS bf16* Aq = (LAS bf16*)lds;
;     LAS bf16* Bc = (LAS bf16*)(lds + 25600);
;     LAS bf16* Kt = (LAS bf16*)(lds + 38400);
;     const int wave = tid >> 6, lane = tid & 63, l15 = lane & 15, quad = lane >> 4;
;     f32x4 S[2] = {(f32x4){0.f, 0.f, 0.f, 0.f}, (f32x4){0.f, 0.f, 0.f, 0.f}};
;     *(LAS u32x4*)(Bc + (tid >> 4) * 200 + (tid & 15) * 8) = (u32x4){0u, 0u, 0u, 0u};
;     u32x4 rq0A, rq1A, rsA, rk0A, rk1A, rvA = (u32x4){0u, 0u, 0u, 0u}; f32x4 rdA;
;     u32x4 rq0B, rq1B, rsB, rk0B, rk1B, rvB = (u32x4){0u, 0u, 0u, 0u}; f32x4 rdB;
.Lp3V_item:
	s_lshr_b32 s4, s3, 3
	s_and_b32 s41, s4, 7
	s_lshr_b32 s5, s4, 3
	s_and_b32 s37, s3, 7
	s_lshl_b32 s37, s37, 2
	s_add_i32 s37, s37, s5
	s_lshr_b32 s39, s37, 2
	s_and_b32 s40, s37, 3
	s_add_u32 s8, s94, 0x1d800000
	s_addc_u32 s9, s95, 0
	s_lshl_b32 s31, s39, 21
	s_add_u32 s8, s8, s31
	s_addc_u32 s9, s9, 0
	s_lshl_b32 s31, s40, 8
	s_add_u32 s8, s8, s31
	s_addc_u32 s9, s9, 0
	s_add_u32 s10, s94, 0x2f00000
	s_addc_u32 s11, s95, 0
	s_lshl_b32 s31, s37, 18
	s_add_u32 s10, s10, s31
	s_addc_u32 s11, s11, 0
	s_add_u32 s12, s94, 0x3700000
	s_addc_u32 s13, s95, 0
	s_lshl_b32 s31, s37, 19
	s_add_u32 s12, s12, s31
	s_addc_u32 s13, s13, 0
	s_add_u32 s14, s94, 0xd402000
	s_addc_u32 s15, s95, 0
	s_lshl_b32 s31, s39, 25
	s_add_u32 s14, s14, s31
	s_addc_u32 s15, s15, 0
	s_lshl_b32 s31, s40, 9
	s_add_u32 s14, s14, s31
	s_addc_u32 s15, s15, 0
	s_lshl_b32 s31, s41, 6
	s_add_u32 s14, s14, s31
	s_addc_u32 s15, s15, 0
	ds_write_b128 v251, v[8:11]
	s_mov_b32 m0, s46
	s_nop 0
	global_load_lds_dwordx4 v201, s[8:9]
	s_add_i32 m0, s46, 0x400
	s_nop 0
	global_load_lds_dwordx4 v200, s[8:9]
	s_mov_b32 m0, s47
	s_nop 0
	global_load_lds_dwordx4 v197, s[10:11]
	s_mov_b32 m0, s48
	s_nop 0
	global_load_lds_dwordx4 v195, s[12:13]
	s_add_i32 m0, s48, 0x400
	s_nop 0
	global_load_lds_dwordx4 v194, s[12:13]
	s_add_i32 m0, s46, 0x800
	s_nop 0
	global_load_lds_dwordx4 v199, s[8:9]
	s_add_i32 m0, s46, 0xc00
	s_nop 0
	global_load_lds_dwordx4 v198, s[8:9]
	s_add_i32 m0, s47, 0x400
	s_nop 0
	global_load_lds_dwordx4 v196, s[10:11]
	s_add_i32 m0, s48, 0x800
	s_nop 0
	global_load_lds_dwordx4 v193, s[12:13]
	s_add_i32 m0, s48, 0xc00
	s_nop 0
	global_load_lds_dwordx4 v192, s[12:13]
	s_add_u32 s8, s8, 0x10000
	s_addc_u32 s9, s9, 0
	s_add_u32 s10, s10, 0x2000
	s_addc_u32 s11, s11, 0
	s_add_u32 s12, s12, 0x4000
	s_addc_u32 s13, s13, 0
	s_add_i32 m0, s46, 0xa000
	s_nop 0
	global_load_lds_dwordx4 v201, s[8:9]
	s_add_i32 m0, s46, 0xa400
	s_nop 0
	global_load_lds_dwordx4 v200, s[8:9]
	s_add_i32 m0, s47, 0xa000
	s_nop 0
	global_load_lds_dwordx4 v197, s[10:11]
	s_add_i32 m0, s48, 0xa000
	s_nop 0
	global_load_lds_dwordx4 v195, s[12:13]
	s_add_i32 m0, s48, 0xa400
	s_nop 0
	global_load_lds_dwordx4 v194, s[12:13]
	s_add_i32 m0, s46, 0xa800
	s_nop 0
	global_load_lds_dwordx4 v199, s[8:9]
	s_add_i32 m0, s46, 0xac00
	s_nop 0
	global_load_lds_dwordx4 v198, s[8:9]
	s_add_i32 m0, s47, 0xa400
	s_nop 0
	global_load_lds_dwordx4 v196, s[10:11]
	s_add_i32 m0, s48, 0xa800
	s_nop 0
	global_load_lds_dwordx4 v193, s[12:13]
	s_add_i32 m0, s48, 0xac00
	s_nop 0
	global_load_lds_dwordx4 v192, s[12:13]
	s_add_u32 s8, s8, 0x10000
	s_addc_u32 s9, s9, 0
	s_add_u32 s10, s10, 0x2000
	s_addc_u32 s11, s11, 0
	s_add_u32 s12, s12, 0x4000
	s_addc_u32 s13, s13, 0
	global_load_dwordx4 v[12:15], v255, s[14:15]
	s_add_u32 s14, s14, 0x100000
	s_addc_u32 s15, s15, 0
	global_load_dwordx4 v[16:19], v255, s[14:15]
	s_add_u32 s14, s14, 0x100000
	s_addc_u32 s15, s15, 0
	global_load_dwordx4 v[20:23], v255, s[14:15]
	s_add_u32 s14, s14, 0x100000
	s_addc_u32 s15, s15, 0
	s_waitcnt vmcnt(0)
	ds_write_b16 v216, v12 offset:0
	ds_write_b16_d16_hi v215, v12 offset:0
	ds_write_b16 v214, v13 offset:0
	ds_write_b16_d16_hi v213, v13 offset:0
	ds_write_b16 v212, v14 offset:0
	ds_write_b16_d16_hi v211, v14 offset:0
	ds_write_b16 v210, v15 offset:0
	ds_write_b16_d16_hi v209, v15 offset:0
	s_mov_b32 s33, 0
	s_waitcnt lgkmcnt(0)
	s_barrier
.Lp3V_loop:
	s_waitcnt vmcnt(11)
	ds_write_b16 v216, v16 offset:12288
	ds_write_b16_d16_hi v215, v16 offset:12288
	ds_write_b16 v214, v17 offset:12288
	ds_write_b16_d16_hi v213, v17 offset:12288
	ds_write_b16 v212, v18 offset:12288
	ds_write_b16_d16_hi v211, v18 offset:12288
	ds_write_b16 v210, v19 offset:12288
	ds_write_b16_d16_hi v209, v19 offset:12288
	s_add_i32 m0, s46, 0x14000
	s_nop 0
	global_load_lds_dwordx4 v201, s[8:9]
	s_add_i32 m0, s46, 0x14400
	s_nop 0
	global_load_lds_dwordx4 v200, s[8:9]
	s_add_i32 m0, s47, 0x14000
	s_nop 0
	global_load_lds_dwordx4 v197, s[10:11]
	s_add_i32 m0, s48, 0x14000
	s_nop 0
	global_load_lds_dwordx4 v195, s[12:13]
	s_add_i32 m0, s48, 0x14400
	s_nop 0
	global_load_lds_dwordx4 v194, s[12:13]
	s_add_i32 m0, s46, 0x14800
	s_nop 0
	global_load_lds_dwordx4 v199, s[8:9]
	s_add_i32 m0, s46, 0x14c00
	s_nop 0
	global_load_lds_dwordx4 v198, s[8:9]
	s_add_i32 m0, s47, 0x14400
	s_nop 0
	global_load_lds_dwordx4 v196, s[10:11]
	s_add_i32 m0, s48, 0x14800
	s_nop 0
	global_load_lds_dwordx4 v193, s[12:13]
	s_add_i32 m0, s48, 0x14c00
	s_nop 0
	global_load_lds_dwordx4 v192, s[12:13]
	s_cmp_lt_u32 s33, 29
	s_cselect_b32 s43, 0x10000, 0
	s_add_u32 s8, s8, s43
	s_addc_u32 s9, s9, 0
	s_cmp_lt_u32 s33, 29
	s_cselect_b32 s43, 0x2000, 0
	s_add_u32 s10, s10, s43
	s_addc_u32 s11, s11, 0
	s_cmp_lt_u32 s33, 29
	s_cselect_b32 s43, 0x4000, 0
	s_add_u32 s12, s12, s43
	s_addc_u32 s13, s13, 0
	global_load_dwordx4 v[12:15], v255, s[14:15]
	s_cmp_lt_u32 s33, 28
	s_cselect_b32 s43, 0x100000, 0
	s_add_u32 s14, s14, s43
	s_addc_u32 s15, s15, 0
	s_add_i32 s33, s33, 1
	s_waitcnt vmcnt(12)
	s_waitcnt lgkmcnt(0)
	s_barrier
	s_waitcnt vmcnt(11)
	ds_write_b16 v216, v20 offset:0
	ds_write_b16_d16_hi v215, v20 offset:0
	ds_write_b16 v214, v21 offset:0
	ds_write_b16_d16_hi v213, v21 offset:0
	ds_write_b16 v212, v22 offset:0
	ds_write_b16_d16_hi v211, v22 offset:0
	ds_write_b16 v210, v23 offset:0
	ds_write_b16_d16_hi v209, v23 offset:0
	s_mov_b32 m0, s46
	s_nop 0
	global_load_lds_dwordx4 v201, s[8:9]
	s_add_i32 m0, s46, 0x400
	s_nop 0
	global_load_lds_dwordx4 v200, s[8:9]
	s_mov_b32 m0, s47
	s_nop 0
	global_load_lds_dwordx4 v197, s[10:11]
	s_mov_b32 m0, s48
	s_nop 0
	global_load_lds_dwordx4 v195, s[12:13]
	s_add_i32 m0, s48, 0x400
	s_nop 0
	global_load_lds_dwordx4 v194, s[12:13]
	s_add_i32 m0, s46, 0x800
	s_nop 0
	global_load_lds_dwordx4 v199, s[8:9]
	s_add_i32 m0, s46, 0xc00
	s_nop 0
	global_load_lds_dwordx4 v198, s[8:9]
	s_add_i32 m0, s47, 0x400
	s_nop 0
	global_load_lds_dwordx4 v196, s[10:11]
	s_add_i32 m0, s48, 0x800
	s_nop 0
	global_load_lds_dwordx4 v193, s[12:13]
	s_add_i32 m0, s48, 0xc00
	s_nop 0
	global_load_lds_dwordx4 v192, s[12:13]
	s_cmp_lt_u32 s33, 29
	s_cselect_b32 s43, 0x10000, 0
	s_add_u32 s8, s8, s43
	s_addc_u32 s9, s9, 0
	s_cmp_lt_u32 s33, 29
	s_cselect_b32 s43, 0x2000, 0
	s_add_u32 s10, s10, s43
	s_addc_u32 s11, s11, 0
	s_cmp_lt_u32 s33, 29
	s_cselect_b32 s43, 0x4000, 0
	s_add_u32 s12, s12, s43
	s_addc_u32 s13, s13, 0
	global_load_dwordx4 v[16:19], v255, s[14:15]
	s_cmp_lt_u32 s33, 28
	s_cselect_b32 s43, 0x100000, 0
	s_add_u32 s14, s14, s43
	s_addc_u32 s15, s15, 0
	s_add_i32 s33, s33, 1
	s_waitcnt vmcnt(12)
	s_waitcnt lgkmcnt(0)
	s_barrier
	s_waitcnt vmcnt(11)
	ds_write_b16 v216, v12 offset:12288
	ds_write_b16_d16_hi v215, v12 offset:12288
	ds_write_b16 v214, v13 offset:12288
	ds_write_b16_d16_hi v213, v13 offset:12288
	ds_write_b16 v212, v14 offset:12288
	ds_write_b16_d16_hi v211, v14 offset:12288
	ds_write_b16 v210, v15 offset:12288
	ds_write_b16_d16_hi v209, v15 offset:12288
	s_add_i32 m0, s46, 0xa000
	s_nop 0
	global_load_lds_dwordx4 v201, s[8:9]
	s_add_i32 m0, s46, 0xa400
	s_nop 0
	global_load_lds_dwordx4 v200, s[8:9]
	s_add_i32 m0, s47, 0xa000
	s_nop 0
	global_load_lds_dwordx4 v197, s[10:11]
	s_add_i32 m0, s48, 0xa000
	s_nop 0
	global_load_lds_dwordx4 v195, s[12:13]
	s_add_i32 m0, s48, 0xa400
	s_nop 0
	global_load_lds_dwordx4 v194, s[12:13]
	s_add_i32 m0, s46, 0xa800
	s_nop 0
	global_load_lds_dwordx4 v199, s[8:9]
	s_add_i32 m0, s46, 0xac00
	s_nop 0
	global_load_lds_dwordx4 v198, s[8:9]
	s_add_i32 m0, s47, 0xa400
	s_nop 0
	global_load_lds_dwordx4 v196, s[10:11]
	s_add_i32 m0, s48, 0xa800
	s_nop 0
	global_load_lds_dwordx4 v193, s[12:13]
	s_add_i32 m0, s48, 0xac00
	s_nop 0
	global_load_lds_dwordx4 v192, s[12:13]
	s_cmp_lt_u32 s33, 29
	s_cselect_b32 s43, 0x10000, 0
	s_add_u32 s8, s8, s43
	s_addc_u32 s9, s9, 0
	s_cmp_lt_u32 s33, 29
	s_cselect_b32 s43, 0x2000, 0
	s_add_u32 s10, s10, s43
	s_addc_u32 s11, s11, 0
	s_cmp_lt_u32 s33, 29
	s_cselect_b32 s43, 0x4000, 0
	s_add_u32 s12, s12, s43
	s_addc_u32 s13, s13, 0
	global_load_dwordx4 v[20:23], v255, s[14:15]
	s_cmp_lt_u32 s33, 28
	s_cselect_b32 s43, 0x100000, 0
	s_add_u32 s14, s14, s43
	s_addc_u32 s15, s15, 0
	s_add_i32 s33, s33, 1
	s_waitcnt vmcnt(12)
	s_waitcnt lgkmcnt(0)
	s_barrier
	s_waitcnt vmcnt(11)
	ds_write_b16 v216, v16 offset:0
	ds_write_b16_d16_hi v215, v16 offset:0
	ds_write_b16 v214, v17 offset:0
	ds_write_b16_d16_hi v213, v17 offset:0
	ds_write_b16 v212, v18 offset:0
	ds_write_b16_d16_hi v211, v18 offset:0
	ds_write_b16 v210, v19 offset:0
	ds_write_b16_d16_hi v209, v19 offset:0
	s_add_i32 m0, s46, 0x14000
	s_nop 0
	global_load_lds_dwordx4 v201, s[8:9]
	s_add_i32 m0, s46, 0x14400
	s_nop 0
	global_load_lds_dwordx4 v200, s[8:9]
	s_add_i32 m0, s47, 0x14000
	s_nop 0
	global_load_lds_dwordx4 v197, s[10:11]
	s_add_i32 m0, s48, 0x14000
	s_nop 0
	global_load_lds_dwordx4 v195, s[12:13]
	s_add_i32 m0, s48, 0x14400
	s_nop 0
	global_load_lds_dwordx4 v194, s[12:13]
	s_add_i32 m0, s46, 0x14800
	s_nop 0
	global_load_lds_dwordx4 v199, s[8:9]
	s_add_i32 m0, s46, 0x14c00
	s_nop 0
	global_load_lds_dwordx4 v198, s[8:9]
	s_add_i32 m0, s47, 0x14400
	s_nop 0
	global_load_lds_dwordx4 v196, s[10:11]
	s_add_i32 m0, s48, 0x14800
	s_nop 0
	global_load_lds_dwordx4 v193, s[12:13]
	s_add_i32 m0, s48, 0x14c00
	s_nop 0
	global_load_lds_dwordx4 v192, s[12:13]
	s_cmp_lt_u32 s33, 29
	s_cselect_b32 s43, 0x10000, 0
	s_add_u32 s8, s8, s43
	s_addc_u32 s9, s9, 0
	s_cmp_lt_u32 s33, 29
	s_cselect_b32 s43, 0x2000, 0
	s_add_u32 s10, s10, s43
	s_addc_u32 s11, s11, 0
	s_cmp_lt_u32 s33, 29
	s_cselect_b32 s43, 0x4000, 0
	s_add_u32 s12, s12, s43
	s_addc_u32 s13, s13, 0
	global_load_dwordx4 v[12:15], v255, s[14:15]
	s_cmp_lt_u32 s33, 28
	s_cselect_b32 s43, 0x100000, 0
	s_add_u32 s14, s14, s43
	s_addc_u32 s15, s15, 0
	s_add_i32 s33, s33, 1
	s_waitcnt vmcnt(12)
	s_waitcnt lgkmcnt(0)
	s_barrier
	s_waitcnt vmcnt(11)
	ds_write_b16 v216, v20 offset:12288
	ds_write_b16_d16_hi v215, v20 offset:12288
	ds_write_b16 v214, v21 offset:12288
	ds_write_b16_d16_hi v213, v21 offset:12288
	ds_write_b16 v212, v22 offset:12288
	ds_write_b16_d16_hi v211, v22 offset:12288
	ds_write_b16 v210, v23 offset:12288
	ds_write_b16_d16_hi v209, v23 offset:12288
	s_mov_b32 m0, s46
	s_nop 0
	global_load_lds_dwordx4 v201, s[8:9]
	s_add_i32 m0, s46, 0x400
	s_nop 0
	global_load_lds_dwordx4 v200, s[8:9]
	s_mov_b32 m0, s47
	s_nop 0
	global_load_lds_dwordx4 v197, s[10:11]
	s_mov_b32 m0, s48
	s_nop 0
	global_load_lds_dwordx4 v195, s[12:13]
	s_add_i32 m0, s48, 0x400
	s_nop 0
	global_load_lds_dwordx4 v194, s[12:13]
	s_add_i32 m0, s46, 0x800
	s_nop 0
	global_load_lds_dwordx4 v199, s[8:9]
	s_add_i32 m0, s46, 0xc00
	s_nop 0
	global_load_lds_dwordx4 v198, s[8:9]
	s_add_i32 m0, s47, 0x400
	s_nop 0
	global_load_lds_dwordx4 v196, s[10:11]
	s_add_i32 m0, s48, 0x800
	s_nop 0
	global_load_lds_dwordx4 v193, s[12:13]
	s_add_i32 m0, s48, 0xc00
	s_nop 0
	global_load_lds_dwordx4 v192, s[12:13]
	s_cmp_lt_u32 s33, 29
	s_cselect_b32 s43, 0x10000, 0
	s_add_u32 s8, s8, s43
	s_addc_u32 s9, s9, 0
	s_cmp_lt_u32 s33, 29
	s_cselect_b32 s43, 0x2000, 0
	s_add_u32 s10, s10, s43
	s_addc_u32 s11, s11, 0
	s_cmp_lt_u32 s33, 29
	s_cselect_b32 s43, 0x4000, 0
	s_add_u32 s12, s12, s43
	s_addc_u32 s13, s13, 0
	global_load_dwordx4 v[16:19], v255, s[14:15]
	s_cmp_lt_u32 s33, 28
	s_cselect_b32 s43, 0x100000, 0
	s_add_u32 s14, s14, s43
	s_addc_u32 s15, s15, 0
	s_add_i32 s33, s33, 1
	s_waitcnt vmcnt(12)
	s_waitcnt lgkmcnt(0)
	s_barrier
	s_waitcnt vmcnt(11)
	ds_write_b16 v216, v12 offset:0
	ds_write_b16_d16_hi v215, v12 offset:0
	ds_write_b16 v214, v13 offset:0
	ds_write_b16_d16_hi v213, v13 offset:0
	ds_write_b16 v212, v14 offset:0
	ds_write_b16_d16_hi v211, v14 offset:0
	ds_write_b16 v210, v15 offset:0
	ds_write_b16_d16_hi v209, v15 offset:0
	s_add_i32 m0, s46, 0xa000
	s_nop 0
	global_load_lds_dwordx4 v201, s[8:9]
	s_add_i32 m0, s46, 0xa400
	s_nop 0
	global_load_lds_dwordx4 v200, s[8:9]
	s_add_i32 m0, s47, 0xa000
	s_nop 0
	global_load_lds_dwordx4 v197, s[10:11]
	s_add_i32 m0, s48, 0xa000
	s_nop 0
	global_load_lds_dwordx4 v195, s[12:13]
	s_add_i32 m0, s48, 0xa400
	s_nop 0
	global_load_lds_dwordx4 v194, s[12:13]
	s_add_i32 m0, s46, 0xa800
	s_nop 0
	global_load_lds_dwordx4 v199, s[8:9]
	s_add_i32 m0, s46, 0xac00
	s_nop 0
	global_load_lds_dwordx4 v198, s[8:9]
	s_add_i32 m0, s47, 0xa400
	s_nop 0
	global_load_lds_dwordx4 v196, s[10:11]
	s_add_i32 m0, s48, 0xa800
	s_nop 0
	global_load_lds_dwordx4 v193, s[12:13]
	s_add_i32 m0, s48, 0xac00
	s_nop 0
	global_load_lds_dwordx4 v192, s[12:13]
	s_cmp_lt_u32 s33, 29
	s_cselect_b32 s43, 0x10000, 0
	s_add_u32 s8, s8, s43
	s_addc_u32 s9, s9, 0
	s_cmp_lt_u32 s33, 29
	s_cselect_b32 s43, 0x2000, 0
	s_add_u32 s10, s10, s43
	s_addc_u32 s11, s11, 0
	s_cmp_lt_u32 s33, 29
	s_cselect_b32 s43, 0x4000, 0
	s_add_u32 s12, s12, s43
	s_addc_u32 s13, s13, 0
	global_load_dwordx4 v[20:23], v255, s[14:15]
	s_cmp_lt_u32 s33, 28
	s_cselect_b32 s43, 0x100000, 0
	s_add_u32 s14, s14, s43
	s_addc_u32 s15, s15, 0
	s_add_i32 s33, s33, 1
	s_waitcnt vmcnt(12)
	s_waitcnt lgkmcnt(0)
	s_barrier
	s_cmp_lt_u32 s33, 30
	s_cbranch_scc1 .Lp3V_loop
	s_waitcnt vmcnt(11)
	ds_write_b16 v216, v16 offset:12288
	ds_write_b16_d16_hi v215, v16 offset:12288
	ds_write_b16 v214, v17 offset:12288
	ds_write_b16_d16_hi v213, v17 offset:12288
	ds_write_b16 v212, v18 offset:12288
	ds_write_b16_d16_hi v211, v18 offset:12288
	ds_write_b16 v210, v19 offset:12288
	ds_write_b16_d16_hi v209, v19 offset:12288
	s_add_i32 m0, s46, 0x14000
	s_nop 0
	global_load_lds_dwordx4 v201, s[8:9]
	s_add_i32 m0, s46, 0x14400
	s_nop 0
	global_load_lds_dwordx4 v200, s[8:9]
	s_add_i32 m0, s47, 0x14000
	s_nop 0
	global_load_lds_dwordx4 v197, s[10:11]
	s_add_i32 m0, s48, 0x14000
	s_nop 0
	global_load_lds_dwordx4 v195, s[12:13]
	s_add_i32 m0, s48, 0x14400
	s_nop 0
	global_load_lds_dwordx4 v194, s[12:13]
	s_add_i32 m0, s46, 0x14800
	s_nop 0
	global_load_lds_dwordx4 v199, s[8:9]
	s_add_i32 m0, s46, 0x14c00
	s_nop 0
	global_load_lds_dwordx4 v198, s[8:9]
	s_add_i32 m0, s47, 0x14400
	s_nop 0
	global_load_lds_dwordx4 v196, s[10:11]
	s_add_i32 m0, s48, 0x14800
	s_nop 0
	global_load_lds_dwordx4 v193, s[12:13]
	s_add_i32 m0, s48, 0x14c00
	s_nop 0
	global_load_lds_dwordx4 v192, s[12:13]
	s_cmp_lt_u32 s33, 29
	s_cselect_b32 s43, 0x10000, 0
	s_add_u32 s8, s8, s43
	s_addc_u32 s9, s9, 0
	s_cmp_lt_u32 s33, 29
	s_cselect_b32 s43, 0x2000, 0
	s_add_u32 s10, s10, s43
	s_addc_u32 s11, s11, 0
	s_cmp_lt_u32 s33, 29
	s_cselect_b32 s43, 0x4000, 0
	s_add_u32 s12, s12, s43
	s_addc_u32 s13, s13, 0
	global_load_dwordx4 v[12:15], v255, s[14:15]
	s_cmp_lt_u32 s33, 28
	s_cselect_b32 s43, 0x100000, 0
	s_add_u32 s14, s14, s43
	s_addc_u32 s15, s15, 0
	s_add_i32 s33, s33, 1
	s_waitcnt vmcnt(12)
	s_waitcnt lgkmcnt(0)
	s_barrier
	s_waitcnt vmcnt(11)
	ds_write_b16 v216, v20 offset:0
	ds_write_b16_d16_hi v215, v20 offset:0
	ds_write_b16 v214, v21 offset:0
	ds_write_b16_d16_hi v213, v21 offset:0
	ds_write_b16 v212, v22 offset:0
	ds_write_b16_d16_hi v211, v22 offset:0
	ds_write_b16 v210, v23 offset:0
	ds_write_b16_d16_hi v209, v23 offset:0
	s_mov_b32 m0, s46
	s_nop 0
	global_load_lds_dwordx4 v201, s[8:9]
	s_add_i32 m0, s46, 0x400
	s_nop 0
	global_load_lds_dwordx4 v200, s[8:9]
	s_mov_b32 m0, s47
	s_nop 0
	global_load_lds_dwordx4 v197, s[10:11]
	s_mov_b32 m0, s48
	s_nop 0
	global_load_lds_dwordx4 v195, s[12:13]
	s_add_i32 m0, s48, 0x400
	s_nop 0
	global_load_lds_dwordx4 v194, s[12:13]
	s_add_i32 m0, s46, 0x800
	s_nop 0
	global_load_lds_dwordx4 v199, s[8:9]
	s_add_i32 m0, s46, 0xc00
	s_nop 0
	global_load_lds_dwordx4 v198, s[8:9]
	s_add_i32 m0, s47, 0x400
	s_nop 0
	global_load_lds_dwordx4 v196, s[10:11]
	s_add_i32 m0, s48, 0x800
	s_nop 0
	global_load_lds_dwordx4 v193, s[12:13]
	s_add_i32 m0, s48, 0xc00
	s_nop 0
	global_load_lds_dwordx4 v192, s[12:13]
	s_cmp_lt_u32 s33, 29
	s_cselect_b32 s43, 0x10000, 0
	s_add_u32 s8, s8, s43
	s_addc_u32 s9, s9, 0
	s_cmp_lt_u32 s33, 29
	s_cselect_b32 s43, 0x2000, 0
	s_add_u32 s10, s10, s43
	s_addc_u32 s11, s11, 0
	s_cmp_lt_u32 s33, 29
	s_cselect_b32 s43, 0x4000, 0
	s_add_u32 s12, s12, s43
	s_addc_u32 s13, s13, 0
	global_load_dwordx4 v[16:19], v255, s[14:15]
	s_cmp_lt_u32 s33, 28
	s_cselect_b32 s43, 0x100000, 0
	s_add_u32 s14, s14, s43
	s_addc_u32 s15, s15, 0
	s_add_i32 s33, s33, 1
	s_waitcnt vmcnt(12)
	s_waitcnt lgkmcnt(0)
	s_barrier
	s_waitcnt vmcnt(0) lgkmcnt(0)
	s_barrier
	s_add_i32 s3, s3, s42
	s_cmpk_lt_i32 s3, 0x100
	s_cbranch_scc1 .Lp3V_item
	s_branch .Lp3_done
